# ssq ladder row reductions: the two ds_bpermute LDS round trips per row (shfl_xor 16 / 32) replaced by v_permlane16_swap / v_permlane32_swap on a copy (VALU only, bit-identical) in the four GEMM epilog
# speedup vs baseline: 1.0293x; 1.0101x over previous
; __device__ __forceinline__ float row_rstd16_coop(const float* ssq, int row, int fq, float inv_n) {
;     const f32x4 a = *(const f32x4*)(ssq + (size_t)row * 16 + fq * 4);
;     float s = (a[0] + a[1]) + (a[2] + a[3]);
;     s += __shfl_xor(s, 16); s += __shfl_xor(s, 32);
;     return __builtin_amdgcn_rsqf(s * inv_n + EPS);
;     __device__ __forceinline__ void operator()(const f32x4 (&acc)[2][2][4][2], const Unit& u, int wr, int wc, int fr, int fq) const {
;     ...
;         for (int ai = 0; ai < 2; ++ai) {
; #pragma unroll
;             for (int m = 0; m < 4; ++m) rsv[ai][m] = row_rstd16_coop(ssq, row0 + ai * HALF + m * 16, fq, 1.0f / 1024.0f);
;         }
; #pragma unroll
;         for (int ai = 0; ai < 2; ++ai)
; #pragma unroll
;             for (int m = 0; m < 4; ++m) {
;                 const int row = row0 + ai * HALF + m * 16;
;                 const float rs = rsv[ai][m];
;                 bf16_t* rowp = H + (size_t)row * ldh + (col0 >> 1);
; #pragma unroll
;                 for (int bj = 0; bj < 2; ++bj) {
;                     const f32x4 v0 = acc[ai][bj][m][0] * rs, v1 = acc[ai][bj][m][1] * rs;
.LBB0_3168:
	v_lshl_add_u32 v156, s58, 8, v1
	v_ashrrev_i32_e32 v157, 31, v156
	v_lshlrev_b64 v[130:131], 6, v[156:157]
	v_lshl_add_u64 v[130:131], v[142:143], 0, v[130:131]
	global_load_dwordx4 v[182:185], v[130:131], off offset:1024
	global_load_dwordx4 v[186:189], v[130:131], off offset:2048
	global_load_dwordx4 v[190:193], v[130:131], off offset:3072
	v_add_co_u32_e32 v210, vcc, 0x2000, v130
	s_nop 1
	v_addc_co_u32_e32 v211, vcc, 0, v131, vcc
	global_load_dwordx4 v[194:197], v[210:211], off
	global_load_dwordx4 v[198:201], v[210:211], off offset:1024
	global_load_dwordx4 v[202:205], v[210:211], off offset:2048
	global_load_dwordx4 v[206:209], v[210:211], off offset:3072
	global_load_dwordx4 v[130:133], v[130:131], off
	v_or_b32_e32 v174, 16, v156
	v_ashrrev_i32_e32 v175, 31, v174
	v_or_b32_e32 v170, 32, v156
	v_ashrrev_i32_e32 v171, 31, v170
	v_or_b32_e32 v166, 48, v156
	v_ashrrev_i32_e32 v167, 31, v166
	v_add_u32_e32 v162, 0x80, v156
	v_ashrrev_i32_e32 v163, 31, v162
	v_add_u32_e32 v158, 0x90, v156
	v_ashrrev_i32_e32 v159, 31, v158
	v_add_u32_e32 v152, 0xa0, v156
	v_ashrrev_i32_e32 v153, 31, v152
	s_and_b64 vcc, exec, s[4:5]
	s_waitcnt vmcnt(0)
	v_mov_b32_e32 v148, v131
	v_mov_b32_e32 v149, v132
	v_mov_b32_e32 v131, v133
	v_pk_add_f32 v[130:131], v[148:149], v[130:131]
	s_nop 0
	v_add_f32_e32 v130, v130, v131
	v_mov_b32_e32 v131, v130
	s_nop 1
	v_permlane16_swap_b32 v131, v130
	s_waitcnt lgkmcnt(0)
	v_add_f32_e32 v130, v130, v131
	v_mov_b32_e32 v131, v130
	s_nop 1
	v_permlane32_swap_b32 v131, v130
	s_waitcnt lgkmcnt(0)
	v_add_f32_e32 v130, v130, v131
	v_fmamk_f32 v130, v130, 0x3a800000, v231
	v_rsq_f32_e32 v176, v130
	s_nop 1
	v_pk_mul_f32 v[122:123], v[122:123], v[176:177] op_sel_hi:[1,0]
	v_pk_mul_f32 v[124:125], v[124:125], v[176:177] op_sel_hi:[1,0]
	v_pk_mul_f32 v[126:127], v[126:127], v[176:177] op_sel_hi:[1,0]
	v_pk_mul_f32 v[128:129], v[128:129], v[176:177] op_sel_hi:[1,0]
	v_pk_mul_f32 v[118:119], v[118:119], v[176:177] op_sel_hi:[1,0]
	v_pk_mul_f32 v[120:121], v[120:121], v[176:177] op_sel_hi:[1,0]
	v_pk_mul_f32 v[114:115], v[114:115], v[176:177] op_sel_hi:[1,0]
	v_pk_mul_f32 v[116:117], v[116:117], v[176:177] op_sel_hi:[1,0]
	v_add_f32_e32 v130, v183, v182
	v_add_f32_e32 v131, v184, v185
	s_nop 0
	v_add_f32_e32 v130, v130, v131
	v_mov_b32_e32 v131, v130
	s_nop 1
	v_permlane16_swap_b32 v131, v130
	s_waitcnt lgkmcnt(0)
	v_add_f32_e32 v130, v130, v131
	v_mov_b32_e32 v131, v130
	s_nop 1
	v_permlane32_swap_b32 v131, v130
	s_waitcnt lgkmcnt(0)
	v_add_f32_e32 v130, v130, v131
	v_fmamk_f32 v130, v130, 0x3a800000, v231
	v_rsq_f32_e32 v172, v130
	s_nop 1
	v_pk_mul_f32 v[110:111], v[110:111], v[172:173] op_sel_hi:[1,0]
	v_pk_mul_f32 v[112:113], v[112:113], v[172:173] op_sel_hi:[1,0]
	v_pk_mul_f32 v[106:107], v[106:107], v[172:173] op_sel_hi:[1,0]
	v_pk_mul_f32 v[108:109], v[108:109], v[172:173] op_sel_hi:[1,0]
	v_pk_mul_f32 v[102:103], v[102:103], v[172:173] op_sel_hi:[1,0]
	v_pk_mul_f32 v[104:105], v[104:105], v[172:173] op_sel_hi:[1,0]
	v_pk_mul_f32 v[98:99], v[98:99], v[172:173] op_sel_hi:[1,0]
	v_pk_mul_f32 v[100:101], v[100:101], v[172:173] op_sel_hi:[1,0]
	v_add_f32_e32 v130, v187, v186
	v_add_f32_e32 v131, v188, v189
	s_nop 0
	v_add_f32_e32 v130, v130, v131
	v_mov_b32_e32 v131, v130
	s_nop 1
	v_permlane16_swap_b32 v131, v130
	s_waitcnt lgkmcnt(0)
	v_add_f32_e32 v130, v130, v131
	v_mov_b32_e32 v131, v130
	s_nop 1
	v_permlane32_swap_b32 v131, v130
	s_waitcnt lgkmcnt(0)
	v_add_f32_e32 v130, v130, v131
	v_fmamk_f32 v130, v130, 0x3a800000, v231
	v_rsq_f32_e32 v168, v130
	s_nop 1
	v_pk_mul_f32 v[94:95], v[94:95], v[168:169] op_sel_hi:[1,0]
	v_pk_mul_f32 v[96:97], v[96:97], v[168:169] op_sel_hi:[1,0]
	v_pk_mul_f32 v[90:91], v[90:91], v[168:169] op_sel_hi:[1,0]
	v_pk_mul_f32 v[92:93], v[92:93], v[168:169] op_sel_hi:[1,0]
	v_pk_mul_f32 v[86:87], v[86:87], v[168:169] op_sel_hi:[1,0]
	v_pk_mul_f32 v[88:89], v[88:89], v[168:169] op_sel_hi:[1,0]
	v_pk_mul_f32 v[82:83], v[82:83], v[168:169] op_sel_hi:[1,0]
	v_pk_mul_f32 v[84:85], v[84:85], v[168:169] op_sel_hi:[1,0]
	v_add_f32_e32 v130, v191, v190
	v_add_f32_e32 v131, v192, v193
	s_nop 0
	v_add_f32_e32 v130, v130, v131
	v_mov_b32_e32 v131, v130
	s_nop 1
	v_permlane16_swap_b32 v131, v130
	s_waitcnt lgkmcnt(0)
	v_add_f32_e32 v130, v130, v131
	v_mov_b32_e32 v131, v130
	s_nop 1
	v_permlane32_swap_b32 v131, v130
	s_waitcnt lgkmcnt(0)
	v_add_f32_e32 v130, v130, v131
	v_fmamk_f32 v130, v130, 0x3a800000, v231
	v_rsq_f32_e32 v164, v130
	s_nop 1
	v_pk_mul_f32 v[78:79], v[78:79], v[164:165] op_sel_hi:[1,0]
	v_pk_mul_f32 v[80:81], v[80:81], v[164:165] op_sel_hi:[1,0]
	v_pk_mul_f32 v[74:75], v[74:75], v[164:165] op_sel_hi:[1,0]
	v_pk_mul_f32 v[76:77], v[76:77], v[164:165] op_sel_hi:[1,0]
	v_pk_mul_f32 v[70:71], v[70:71], v[164:165] op_sel_hi:[1,0]
	v_pk_mul_f32 v[72:73], v[72:73], v[164:165] op_sel_hi:[1,0]
	v_pk_mul_f32 v[66:67], v[66:67], v[164:165] op_sel_hi:[1,0]
	v_pk_mul_f32 v[68:69], v[68:69], v[164:165] op_sel_hi:[1,0]
	v_add_f32_e32 v130, v195, v194
	v_add_f32_e32 v131, v196, v197
	s_nop 0
	v_add_f32_e32 v130, v130, v131
	v_mov_b32_e32 v131, v130
	s_nop 1
	v_permlane16_swap_b32 v131, v130
	s_waitcnt lgkmcnt(0)
	v_add_f32_e32 v130, v130, v131
	v_mov_b32_e32 v131, v130
	s_nop 1
	v_permlane32_swap_b32 v131, v130
	s_waitcnt lgkmcnt(0)
; __device__ __forceinline__ unsigned cvt_pk_bf16(float lo, float hi) { unsigned r; asm volatile("v_cvt_pk_bf16_f32 %0, %1, %2" : "=v"(r) : "v"(lo), "v"(hi)); return r; }
;     __device__ __forceinline__ static float sg(float g, float uu) { return g * __builtin_amdgcn_rcpf(1.0f + __builtin_amdgcn_exp2f(-1.4426950408889634f * g)) * uu; }
; __device__ __forceinline__ float row_rstd16_coop(const float* ssq, int row, int fq, float inv_n) {
;     const f32x4 a = *(const f32x4*)(ssq + (size_t)row * 16 + fq * 4);
;     float s = (a[0] + a[1]) + (a[2] + a[3]);
;     s += __shfl_xor(s, 16); s += __shfl_xor(s, 32);
;     return __builtin_amdgcn_rsqf(s * inv_n + EPS);
;     __device__ __forceinline__ void operator()(const f32x4 (&acc)[2][2][4][2], const Unit& u, int wr, int wc, int fr, int fq) const {
;     ...
;         for (int ai = 0; ai < 2; ++ai) {
; #pragma unroll
;             for (int m = 0; m < 4; ++m) rsv[ai][m] = row_rstd16_coop(ssq, row0 + ai * HALF + m * 16, fq, 1.0f / 1024.0f);
;         }
; #pragma unroll
;         for (int ai = 0; ai < 2; ++ai)
; #pragma unroll
;             for (int m = 0; m < 4; ++m) {
;                 const int row = row0 + ai * HALF + m * 16;
;                 const float rs = rsv[ai][m];
;                 bf16_t* rowp = H + (size_t)row * ldh + (col0 >> 1);
; #pragma unroll
;                 for (int bj = 0; bj < 2; ++bj) {
;                     const f32x4 v0 = acc[ai][bj][m][0] * rs, v1 = acc[ai][bj][m][1] * rs;
;                     u32x2 w; w.x = cvt_pk_bf16(sg(v0[0], v0[1]), sg(v0[2], v0[3])); w.y = cvt_pk_bf16(sg(v1[0], v1[1]), sg(v1[2], v1[3]));
;                     *(u32x2*)(rowp + bj * (HALF / 2)) = w;
;                 }
;             }
	v_add_f32_e32 v130, v130, v131
	v_fmamk_f32 v130, v130, 0x3a800000, v231
	v_rsq_f32_e32 v160, v130
	s_nop 1
	v_pk_mul_f32 v[62:63], v[62:63], v[160:161] op_sel_hi:[1,0]
	v_pk_mul_f32 v[64:65], v[64:65], v[160:161] op_sel_hi:[1,0]
	v_pk_mul_f32 v[58:59], v[58:59], v[160:161] op_sel_hi:[1,0]
	v_pk_mul_f32 v[60:61], v[60:61], v[160:161] op_sel_hi:[1,0]
	v_pk_mul_f32 v[54:55], v[54:55], v[160:161] op_sel_hi:[1,0]
	v_pk_mul_f32 v[56:57], v[56:57], v[160:161] op_sel_hi:[1,0]
	v_pk_mul_f32 v[50:51], v[50:51], v[160:161] op_sel_hi:[1,0]
	v_pk_mul_f32 v[52:53], v[52:53], v[160:161] op_sel_hi:[1,0]
	v_add_f32_e32 v130, v199, v198
	v_add_f32_e32 v131, v200, v201
	s_nop 0
	v_add_f32_e32 v130, v130, v131
	v_mov_b32_e32 v131, v130
	s_nop 1
	v_permlane16_swap_b32 v131, v130
	s_waitcnt lgkmcnt(0)
	v_add_f32_e32 v130, v130, v131
	v_mov_b32_e32 v131, v130
	s_nop 1
	v_permlane32_swap_b32 v131, v130
	s_waitcnt lgkmcnt(0)
	v_add_f32_e32 v130, v130, v131
	v_fmamk_f32 v130, v130, 0x3a800000, v231
	v_rsq_f32_e32 v154, v130
	s_nop 1
	v_pk_mul_f32 v[46:47], v[46:47], v[154:155] op_sel_hi:[1,0]
	v_pk_mul_f32 v[48:49], v[48:49], v[154:155] op_sel_hi:[1,0]
	v_pk_mul_f32 v[42:43], v[42:43], v[154:155] op_sel_hi:[1,0]
	v_pk_mul_f32 v[44:45], v[44:45], v[154:155] op_sel_hi:[1,0]
	v_pk_mul_f32 v[38:39], v[38:39], v[154:155] op_sel_hi:[1,0]
	v_pk_mul_f32 v[40:41], v[40:41], v[154:155] op_sel_hi:[1,0]
	v_pk_mul_f32 v[34:35], v[34:35], v[154:155] op_sel_hi:[1,0]
	v_pk_mul_f32 v[36:37], v[36:37], v[154:155] op_sel_hi:[1,0]
	v_add_f32_e32 v130, v203, v202
	v_add_f32_e32 v131, v204, v205
	v_add_u32_e32 v148, 0xb0, v156
	v_add_f32_e32 v130, v130, v131
	v_mov_b32_e32 v131, v130
	s_nop 1
	v_permlane16_swap_b32 v131, v130
	v_ashrrev_i32_e32 v149, 31, v148
	s_waitcnt lgkmcnt(0)
	v_add_f32_e32 v130, v130, v131
	v_mov_b32_e32 v131, v130
	s_nop 1
	v_permlane32_swap_b32 v131, v130
	s_waitcnt lgkmcnt(0)
	v_add_f32_e32 v130, v130, v131
	v_fmamk_f32 v130, v130, 0x3a800000, v231
	v_rsq_f32_e32 v150, v130
	s_nop 1
	v_pk_mul_f32 v[30:31], v[30:31], v[150:151] op_sel_hi:[1,0]
	v_pk_mul_f32 v[32:33], v[32:33], v[150:151] op_sel_hi:[1,0]
	v_pk_mul_f32 v[26:27], v[26:27], v[150:151] op_sel_hi:[1,0]
	v_pk_mul_f32 v[28:29], v[28:29], v[150:151] op_sel_hi:[1,0]
	v_pk_mul_f32 v[22:23], v[22:23], v[150:151] op_sel_hi:[1,0]
	v_pk_mul_f32 v[24:25], v[24:25], v[150:151] op_sel_hi:[1,0]
	v_pk_mul_f32 v[18:19], v[18:19], v[150:151] op_sel_hi:[1,0]
	v_pk_mul_f32 v[20:21], v[20:21], v[150:151] op_sel_hi:[1,0]
	v_add_f32_e32 v130, v207, v206
	v_add_f32_e32 v131, v208, v209
	v_mov_b64_e32 v[132:133], s[22:23]
	v_add_f32_e32 v130, v130, v131
	v_mov_b32_e32 v131, v130
	s_nop 1
	v_permlane16_swap_b32 v131, v130
	v_mad_i64_i32 v[180:181], s[30:31], v156, s96, v[132:133]
	s_waitcnt lgkmcnt(0)
	v_add_f32_e32 v130, v130, v131
	v_mov_b32_e32 v131, v130
	s_nop 1
	v_permlane32_swap_b32 v131, v130
	s_waitcnt lgkmcnt(0)
	v_add_f32_e32 v130, v130, v131
	v_lshl_or_b32 v131, s57, 8, v155
	v_ashrrev_i32_e32 v178, 1, v131
	v_mul_f32_e32 v131, 0xbfb8aa3b, v122
	v_exp_f32_e32 v131, v131
	v_ashrrev_i32_e32 v179, 31, v178
	v_lshlrev_b64 v[156:157], 1, v[178:179]
	v_lshl_add_u64 v[178:179], v[180:181], 0, v[156:157]
	v_add_f32_e32 v131, 1.0, v131
	v_rcp_f32_e32 v131, v131
	v_fmamk_f32 v130, v130, 0x3a800000, v231
	v_rsq_f32_e32 v130, v130
	v_mul_f32_e32 v122, v122, v131
	v_mul_f32_e32 v122, v123, v122
	v_mul_f32_e32 v123, 0xbfb8aa3b, v124
	v_exp_f32_e32 v123, v123
	v_pk_mul_f32 v[14:15], v[14:15], v[130:131] op_sel_hi:[1,0]
	v_pk_mul_f32 v[16:17], v[16:17], v[130:131] op_sel_hi:[1,0]
	v_pk_mul_f32 v[10:11], v[10:11], v[130:131] op_sel_hi:[1,0]
	v_add_f32_e32 v123, 1.0, v123
	v_rcp_f32_e32 v123, v123
	v_pk_mul_f32 v[12:13], v[12:13], v[130:131] op_sel_hi:[1,0]
	v_pk_mul_f32 v[6:7], v[6:7], v[130:131] op_sel_hi:[1,0]
	v_pk_mul_f32 v[8:9], v[8:9], v[130:131] op_sel_hi:[1,0]
	v_mul_f32_e32 v123, v124, v123
	v_mul_f32_e32 v123, v125, v123
	v_cvt_pk_bf16_f32 v122, v122, v123
	v_mul_f32_e32 v123, 0xbfb8aa3b, v126
	v_exp_f32_e32 v123, v123
	v_mul_f32_e32 v124, 0xbfb8aa3b, v128
	v_exp_f32_e32 v124, v124
	v_pk_mul_f32 v[2:3], v[2:3], v[130:131] op_sel_hi:[1,0]
	v_add_f32_e32 v123, 1.0, v123
	v_rcp_f32_e32 v123, v123
	v_add_f32_e32 v124, 1.0, v124
	v_rcp_f32_e32 v124, v124
	v_pk_mul_f32 v[4:5], v[4:5], v[130:131] op_sel_hi:[1,0]
	v_mul_f32_e32 v123, v126, v123
	v_mul_f32_e32 v123, v127, v123
	v_mul_f32_e32 v124, v128, v124
	v_mul_f32_e32 v124, v129, v124
	v_cvt_pk_bf16_f32 v123, v123, v124
	global_store_dwordx2 v[178:179], v[122:123], off
	v_mul_f32_e32 v122, 0xbfb8aa3b, v118
	v_exp_f32_e32 v122, v122
	s_nop 0
	v_add_f32_e32 v122, 1.0, v122
	v_rcp_f32_e32 v122, v122
	s_nop 0
	v_mul_f32_e32 v118, v118, v122
	v_mul_f32_e32 v118, v119, v118
	v_mul_f32_e32 v119, 0xbfb8aa3b, v120
	v_exp_f32_e32 v119, v119
	s_nop 0
	v_add_f32_e32 v119, 1.0, v119
	v_rcp_f32_e32 v119, v119
	s_nop 0
	v_mul_f32_e32 v119, v120, v119
	v_mul_f32_e32 v119, v121, v119
	v_cvt_pk_bf16_f32 v118, v118, v119
	v_mul_f32_e32 v119, 0xbfb8aa3b, v114
	v_exp_f32_e32 v119, v119
	s_nop 0
	v_add_f32_e32 v119, 1.0, v119
	v_rcp_f32_e32 v119, v119
	s_nop 0
	v_mul_f32_e32 v114, v114, v119
	v_mul_f32_e32 v114, v115, v114
	v_mul_f32_e32 v115, 0xbfb8aa3b, v116
	v_exp_f32_e32 v115, v115
	s_nop 0
	v_add_f32_e32 v115, 1.0, v115
	v_rcp_f32_e32 v115, v115
	s_nop 0
	v_mul_f32_e32 v115, v116, v115
	v_mul_f32_e32 v116, 0xbfb8aa3b, v110
	v_exp_f32_e32 v116, v116
	v_mul_f32_e32 v115, v117, v115
	v_cvt_pk_bf16_f32 v119, v114, v115
	global_store_dwordx2 v[178:179], v[118:119], off offset:128
	v_add_f32_e32 v116, 1.0, v116
	v_rcp_f32_e32 v116, v116
	v_mad_i64_i32 v[114:115], s[30:31], v174, s96, v[132:133]
; __device__ __forceinline__ unsigned cvt_pk_bf16(float lo, float hi) { unsigned r; asm volatile("v_cvt_pk_bf16_f32 %0, %1, %2" : "=v"(r) : "v"(lo), "v"(hi)); return r; }
;     __device__ __forceinline__ static float sg(float g, float uu) { return g * __builtin_amdgcn_rcpf(1.0f + __builtin_amdgcn_exp2f(-1.4426950408889634f * g)) * uu; }
;     __device__ __forceinline__ void operator()(const f32x4 (&acc)[2][2][4][2], const Unit& u, int wr, int wc, int fr, int fq) const {
;         const int row0 = u.pm * BM + wr * 64 + fr, col0 = u.pn * BM + wc * 32 + 8 * fq;
;         float rsv[2][4];
; #pragma unroll
;         for (int ai = 0; ai < 2; ++ai) {
; #pragma unroll
;             for (int m = 0; m < 4; ++m) rsv[ai][m] = row_rstd16_coop(ssq, row0 + ai * HALF + m * 16, fq, 1.0f / 1024.0f);
;         }
; #pragma unroll
;         for (int ai = 0; ai < 2; ++ai)
; #pragma unroll
;             for (int m = 0; m < 4; ++m) {
;                 const int row = row0 + ai * HALF + m * 16;
;                 const float rs = rsv[ai][m];
;                 bf16_t* rowp = H + (size_t)row * ldh + (col0 >> 1);
; #pragma unroll
;                 for (int bj = 0; bj < 2; ++bj) {
;                     const f32x4 v0 = acc[ai][bj][m][0] * rs, v1 = acc[ai][bj][m][1] * rs;
;                     u32x2 w; w.x = cvt_pk_bf16(sg(v0[0], v0[1]), sg(v0[2], v0[3])); w.y = cvt_pk_bf16(sg(v1[0], v1[1]), sg(v1[2], v1[3]));
;                     *(u32x2*)(rowp + bj * (HALF / 2)) = w;
;                 }
	v_lshl_add_u64 v[114:115], v[114:115], 0, v[156:157]
	v_mul_f32_e32 v110, v110, v116
	v_mul_f32_e32 v110, v111, v110
	v_mul_f32_e32 v111, 0xbfb8aa3b, v112
	v_exp_f32_e32 v111, v111
	s_nop 0
	v_add_f32_e32 v111, 1.0, v111
	v_rcp_f32_e32 v111, v111
	s_nop 0
	v_mul_f32_e32 v111, v112, v111
	v_mul_f32_e32 v111, v113, v111
	v_cvt_pk_bf16_f32 v110, v110, v111
	v_mul_f32_e32 v111, 0xbfb8aa3b, v106
	v_exp_f32_e32 v111, v111
	s_nop 0
	v_add_f32_e32 v111, 1.0, v111
	v_rcp_f32_e32 v111, v111
	s_nop 0
	v_mul_f32_e32 v106, v106, v111
	v_mul_f32_e32 v106, v107, v106
	v_mul_f32_e32 v107, 0xbfb8aa3b, v108
	v_exp_f32_e32 v107, v107
	s_nop 0
	v_add_f32_e32 v107, 1.0, v107
	v_rcp_f32_e32 v107, v107
	s_nop 0
	v_mul_f32_e32 v107, v108, v107
	v_mul_f32_e32 v107, v109, v107
	v_cvt_pk_bf16_f32 v111, v106, v107
	v_mul_f32_e32 v106, 0xbfb8aa3b, v102
	v_exp_f32_e32 v106, v106
	global_store_dwordx2 v[114:115], v[110:111], off
	v_add_f32_e32 v106, 1.0, v106
	v_rcp_f32_e32 v106, v106
	s_nop 0
	v_mul_f32_e32 v102, v102, v106
	v_mul_f32_e32 v102, v103, v102
	v_mul_f32_e32 v103, 0xbfb8aa3b, v104
	v_exp_f32_e32 v103, v103
	s_nop 0
	v_add_f32_e32 v103, 1.0, v103
	v_rcp_f32_e32 v103, v103
	s_nop 0
	v_mul_f32_e32 v103, v104, v103
	v_mul_f32_e32 v103, v105, v103
	v_cvt_pk_bf16_f32 v102, v102, v103
	v_mul_f32_e32 v103, 0xbfb8aa3b, v98
	v_exp_f32_e32 v103, v103
	s_nop 0
	v_add_f32_e32 v103, 1.0, v103
	v_rcp_f32_e32 v103, v103
	s_nop 0
	v_mul_f32_e32 v98, v98, v103
	v_mul_f32_e32 v98, v99, v98
	v_mul_f32_e32 v99, 0xbfb8aa3b, v100
	v_exp_f32_e32 v99, v99
	s_nop 0
	v_add_f32_e32 v99, 1.0, v99
	v_rcp_f32_e32 v99, v99
	s_nop 0
	v_mul_f32_e32 v99, v100, v99
	v_mul_f32_e32 v100, 0xbfb8aa3b, v94
	v_exp_f32_e32 v100, v100
	v_mul_f32_e32 v99, v101, v99
	v_cvt_pk_bf16_f32 v103, v98, v99
	global_store_dwordx2 v[114:115], v[102:103], off offset:128
	v_add_f32_e32 v100, 1.0, v100
	v_rcp_f32_e32 v100, v100
	v_mad_i64_i32 v[98:99], s[30:31], v170, s96, v[132:133]
	v_lshl_add_u64 v[98:99], v[98:99], 0, v[156:157]
	v_mul_f32_e32 v94, v94, v100
	v_mul_f32_e32 v94, v95, v94
	v_mul_f32_e32 v95, 0xbfb8aa3b, v96
	v_exp_f32_e32 v95, v95
	s_nop 0
	v_add_f32_e32 v95, 1.0, v95
	v_rcp_f32_e32 v95, v95
	s_nop 0
	v_mul_f32_e32 v95, v96, v95
	v_mul_f32_e32 v95, v97, v95
	v_cvt_pk_bf16_f32 v94, v94, v95
	v_mul_f32_e32 v95, 0xbfb8aa3b, v90
	v_exp_f32_e32 v95, v95
	s_nop 0
	v_add_f32_e32 v95, 1.0, v95
	v_rcp_f32_e32 v95, v95
	s_nop 0
	v_mul_f32_e32 v90, v90, v95
	v_mul_f32_e32 v90, v91, v90
	v_mul_f32_e32 v91, 0xbfb8aa3b, v92
	v_exp_f32_e32 v91, v91
	s_nop 0
	v_add_f32_e32 v91, 1.0, v91
	v_rcp_f32_e32 v91, v91
	s_nop 0
	v_mul_f32_e32 v91, v92, v91
	v_mul_f32_e32 v91, v93, v91
	v_cvt_pk_bf16_f32 v95, v90, v91
	v_mul_f32_e32 v90, 0xbfb8aa3b, v86
	v_exp_f32_e32 v90, v90
	global_store_dwordx2 v[98:99], v[94:95], off
	v_add_f32_e32 v90, 1.0, v90
	v_rcp_f32_e32 v90, v90
	s_nop 0
	v_mul_f32_e32 v86, v86, v90
	v_mul_f32_e32 v86, v87, v86
	v_mul_f32_e32 v87, 0xbfb8aa3b, v88
	v_exp_f32_e32 v87, v87
	s_nop 0
	v_add_f32_e32 v87, 1.0, v87
	v_rcp_f32_e32 v87, v87
	s_nop 0
	v_mul_f32_e32 v87, v88, v87
	v_mul_f32_e32 v87, v89, v87
	v_cvt_pk_bf16_f32 v86, v86, v87
	v_mul_f32_e32 v87, 0xbfb8aa3b, v82
	v_exp_f32_e32 v87, v87
	s_nop 0
	v_add_f32_e32 v87, 1.0, v87
	v_rcp_f32_e32 v87, v87
	s_nop 0
	v_mul_f32_e32 v82, v82, v87
	v_mul_f32_e32 v82, v83, v82
	v_mul_f32_e32 v83, 0xbfb8aa3b, v84
	v_exp_f32_e32 v83, v83
	s_nop 0
	v_add_f32_e32 v83, 1.0, v83
	v_rcp_f32_e32 v83, v83
	s_nop 0
	v_mul_f32_e32 v83, v84, v83
	v_mul_f32_e32 v84, 0xbfb8aa3b, v78
	v_exp_f32_e32 v84, v84
	v_mul_f32_e32 v83, v85, v83
	v_cvt_pk_bf16_f32 v87, v82, v83
	global_store_dwordx2 v[98:99], v[86:87], off offset:128
	v_add_f32_e32 v84, 1.0, v84
	v_rcp_f32_e32 v84, v84
	v_mad_i64_i32 v[82:83], s[30:31], v166, s96, v[132:133]
	v_lshl_add_u64 v[82:83], v[82:83], 0, v[156:157]
	v_mul_f32_e32 v78, v78, v84
	v_mul_f32_e32 v78, v79, v78
	v_mul_f32_e32 v79, 0xbfb8aa3b, v80
	v_exp_f32_e32 v79, v79
	s_nop 0
	v_add_f32_e32 v79, 1.0, v79
	v_rcp_f32_e32 v79, v79
	s_nop 0
	v_mul_f32_e32 v79, v80, v79
	v_mul_f32_e32 v79, v81, v79
	v_cvt_pk_bf16_f32 v78, v78, v79
	v_mul_f32_e32 v79, 0xbfb8aa3b, v74
	v_exp_f32_e32 v79, v79
	s_nop 0
	v_add_f32_e32 v79, 1.0, v79
	v_rcp_f32_e32 v79, v79
	s_nop 0
	v_mul_f32_e32 v74, v74, v79
	v_mul_f32_e32 v74, v75, v74
	v_mul_f32_e32 v75, 0xbfb8aa3b, v76
	v_exp_f32_e32 v75, v75
	s_nop 0
	v_add_f32_e32 v75, 1.0, v75
	v_rcp_f32_e32 v75, v75
	s_nop 0
	v_mul_f32_e32 v75, v76, v75
	v_mul_f32_e32 v75, v77, v75
	v_cvt_pk_bf16_f32 v79, v74, v75
	v_mul_f32_e32 v74, 0xbfb8aa3b, v70
	v_exp_f32_e32 v74, v74
	global_store_dwordx2 v[82:83], v[78:79], off
	v_add_f32_e32 v74, 1.0, v74
	v_rcp_f32_e32 v74, v74
	s_nop 0
	v_mul_f32_e32 v70, v70, v74
	v_mul_f32_e32 v70, v71, v70
	v_mul_f32_e32 v71, 0xbfb8aa3b, v72
	v_exp_f32_e32 v71, v71
	s_nop 0
	v_add_f32_e32 v71, 1.0, v71
	v_rcp_f32_e32 v71, v71
	s_nop 0
	v_mul_f32_e32 v71, v72, v71
	v_mul_f32_e32 v71, v73, v71
	v_cvt_pk_bf16_f32 v70, v70, v71
	v_mul_f32_e32 v71, 0xbfb8aa3b, v66
	v_exp_f32_e32 v71, v71
	s_nop 0
	v_add_f32_e32 v71, 1.0, v71
	v_rcp_f32_e32 v71, v71
	s_nop 0
	v_mul_f32_e32 v66, v66, v71
	v_mul_f32_e32 v66, v67, v66
	v_mul_f32_e32 v67, 0xbfb8aa3b, v68
	v_exp_f32_e32 v67, v67
	s_nop 0
	v_add_f32_e32 v67, 1.0, v67
	v_rcp_f32_e32 v67, v67
	s_nop 0
	v_mul_f32_e32 v67, v68, v67
	v_mul_f32_e32 v68, 0xbfb8aa3b, v62
	v_exp_f32_e32 v68, v68
	v_mul_f32_e32 v67, v69, v67
	v_cvt_pk_bf16_f32 v71, v66, v67
	global_store_dwordx2 v[82:83], v[70:71], off offset:128
	v_add_f32_e32 v68, 1.0, v68
	v_rcp_f32_e32 v68, v68
	v_mad_i64_i32 v[66:67], s[30:31], v162, s96, v[132:133]
	v_lshl_add_u64 v[66:67], v[66:67], 0, v[156:157]
; __device__ __forceinline__ unsigned cvt_pk_bf16(float lo, float hi) { unsigned r; asm volatile("v_cvt_pk_bf16_f32 %0, %1, %2" : "=v"(r) : "v"(lo), "v"(hi)); return r; }
;     __device__ __forceinline__ static float sg(float g, float uu) { return g * __builtin_amdgcn_rcpf(1.0f + __builtin_amdgcn_exp2f(-1.4426950408889634f * g)) * uu; }
;     __device__ __forceinline__ void operator()(const f32x4 (&acc)[2][2][4][2], const Unit& u, int wr, int wc, int fr, int fq) const {
;         const int row0 = u.pm * BM + wr * 64 + fr, col0 = u.pn * BM + wc * 32 + 8 * fq;
;         float rsv[2][4];
; #pragma unroll
;         for (int ai = 0; ai < 2; ++ai) {
; #pragma unroll
;             for (int m = 0; m < 4; ++m) rsv[ai][m] = row_rstd16_coop(ssq, row0 + ai * HALF + m * 16, fq, 1.0f / 1024.0f);
;         }
; #pragma unroll
;         for (int ai = 0; ai < 2; ++ai)
; #pragma unroll
;             for (int m = 0; m < 4; ++m) {
;                 const int row = row0 + ai * HALF + m * 16;
;                 const float rs = rsv[ai][m];
;                 bf16_t* rowp = H + (size_t)row * ldh + (col0 >> 1);
; #pragma unroll
;                 for (int bj = 0; bj < 2; ++bj) {
;                     const f32x4 v0 = acc[ai][bj][m][0] * rs, v1 = acc[ai][bj][m][1] * rs;
;                     u32x2 w; w.x = cvt_pk_bf16(sg(v0[0], v0[1]), sg(v0[2], v0[3])); w.y = cvt_pk_bf16(sg(v1[0], v1[1]), sg(v1[2], v1[3]));
;                     *(u32x2*)(rowp + bj * (HALF / 2)) = w;
;                 }
	v_mul_f32_e32 v62, v62, v68
	v_mul_f32_e32 v62, v63, v62
	v_mul_f32_e32 v63, 0xbfb8aa3b, v64
	v_exp_f32_e32 v63, v63
	s_nop 0
	v_add_f32_e32 v63, 1.0, v63
	v_rcp_f32_e32 v63, v63
	s_nop 0
	v_mul_f32_e32 v63, v64, v63
	v_mul_f32_e32 v63, v65, v63
	v_cvt_pk_bf16_f32 v62, v62, v63
	v_mul_f32_e32 v63, 0xbfb8aa3b, v58
	v_exp_f32_e32 v63, v63
	s_nop 0
	v_add_f32_e32 v63, 1.0, v63
	v_rcp_f32_e32 v63, v63
	s_nop 0
	v_mul_f32_e32 v58, v58, v63
	v_mul_f32_e32 v58, v59, v58
	v_mul_f32_e32 v59, 0xbfb8aa3b, v60
	v_exp_f32_e32 v59, v59
	s_nop 0
	v_add_f32_e32 v59, 1.0, v59
	v_rcp_f32_e32 v59, v59
	s_nop 0
	v_mul_f32_e32 v59, v60, v59
	v_mul_f32_e32 v59, v61, v59
	v_cvt_pk_bf16_f32 v63, v58, v59
	v_mul_f32_e32 v58, 0xbfb8aa3b, v54
	v_exp_f32_e32 v58, v58
	global_store_dwordx2 v[66:67], v[62:63], off
	v_add_f32_e32 v58, 1.0, v58
	v_rcp_f32_e32 v58, v58
	s_nop 0
	v_mul_f32_e32 v54, v54, v58
	v_mul_f32_e32 v54, v55, v54
	v_mul_f32_e32 v55, 0xbfb8aa3b, v56
	v_exp_f32_e32 v55, v55
	s_nop 0
	v_add_f32_e32 v55, 1.0, v55
	v_rcp_f32_e32 v55, v55
	s_nop 0
	v_mul_f32_e32 v55, v56, v55
	v_mul_f32_e32 v55, v57, v55
	v_cvt_pk_bf16_f32 v54, v54, v55
	v_mul_f32_e32 v55, 0xbfb8aa3b, v50
	v_exp_f32_e32 v55, v55
	s_nop 0
	v_add_f32_e32 v55, 1.0, v55
	v_rcp_f32_e32 v55, v55
	s_nop 0
	v_mul_f32_e32 v50, v50, v55
	v_mul_f32_e32 v50, v51, v50
	v_mul_f32_e32 v51, 0xbfb8aa3b, v52
	v_exp_f32_e32 v51, v51
	s_nop 0
	v_add_f32_e32 v51, 1.0, v51
	v_rcp_f32_e32 v51, v51
	s_nop 0
	v_mul_f32_e32 v51, v52, v51
	v_mul_f32_e32 v52, 0xbfb8aa3b, v46
	v_exp_f32_e32 v52, v52
	v_mul_f32_e32 v51, v53, v51
	v_cvt_pk_bf16_f32 v55, v50, v51
	global_store_dwordx2 v[66:67], v[54:55], off offset:128
	v_add_f32_e32 v52, 1.0, v52
	v_rcp_f32_e32 v52, v52
	v_mad_i64_i32 v[50:51], s[30:31], v158, s96, v[132:133]
	v_lshl_add_u64 v[50:51], v[50:51], 0, v[156:157]
	v_mul_f32_e32 v46, v46, v52
	v_mul_f32_e32 v46, v47, v46
	v_mul_f32_e32 v47, 0xbfb8aa3b, v48
	v_exp_f32_e32 v47, v47
	s_nop 0
	v_add_f32_e32 v47, 1.0, v47
	v_rcp_f32_e32 v47, v47
	s_nop 0
	v_mul_f32_e32 v47, v48, v47
	v_mul_f32_e32 v47, v49, v47
	v_cvt_pk_bf16_f32 v46, v46, v47
	v_mul_f32_e32 v47, 0xbfb8aa3b, v42
	v_exp_f32_e32 v47, v47
	s_nop 0
	v_add_f32_e32 v47, 1.0, v47
	v_rcp_f32_e32 v47, v47
	s_nop 0
	v_mul_f32_e32 v42, v42, v47
	v_mul_f32_e32 v42, v43, v42
	v_mul_f32_e32 v43, 0xbfb8aa3b, v44
	v_exp_f32_e32 v43, v43
	s_nop 0
	v_add_f32_e32 v43, 1.0, v43
	v_rcp_f32_e32 v43, v43
	s_nop 0
	v_mul_f32_e32 v43, v44, v43
	v_mul_f32_e32 v43, v45, v43
	v_cvt_pk_bf16_f32 v47, v42, v43
	v_mul_f32_e32 v42, 0xbfb8aa3b, v38
	v_exp_f32_e32 v42, v42
	global_store_dwordx2 v[50:51], v[46:47], off
	v_add_f32_e32 v42, 1.0, v42
	v_rcp_f32_e32 v42, v42
	s_nop 0
	v_mul_f32_e32 v38, v38, v42
	v_mul_f32_e32 v38, v39, v38
	v_mul_f32_e32 v39, 0xbfb8aa3b, v40
	v_exp_f32_e32 v39, v39
	s_nop 0
	v_add_f32_e32 v39, 1.0, v39
	v_rcp_f32_e32 v39, v39
	s_nop 0
	v_mul_f32_e32 v39, v40, v39
	v_mul_f32_e32 v39, v41, v39
	v_cvt_pk_bf16_f32 v38, v38, v39
	v_mul_f32_e32 v39, 0xbfb8aa3b, v34
	v_exp_f32_e32 v39, v39
	s_nop 0
	v_add_f32_e32 v39, 1.0, v39
	v_rcp_f32_e32 v39, v39
	s_nop 0
	v_mul_f32_e32 v34, v34, v39
	v_mul_f32_e32 v34, v35, v34
	v_mul_f32_e32 v35, 0xbfb8aa3b, v36
	v_exp_f32_e32 v35, v35
	s_nop 0
	v_add_f32_e32 v35, 1.0, v35
	v_rcp_f32_e32 v35, v35
	s_nop 0
	v_mul_f32_e32 v35, v36, v35
	v_mul_f32_e32 v36, 0xbfb8aa3b, v30
	v_exp_f32_e32 v36, v36
	v_mul_f32_e32 v35, v37, v35
	v_cvt_pk_bf16_f32 v39, v34, v35
	global_store_dwordx2 v[50:51], v[38:39], off offset:128
	v_add_f32_e32 v36, 1.0, v36
	v_rcp_f32_e32 v36, v36
	v_mad_i64_i32 v[34:35], s[30:31], v152, s96, v[132:133]
; __device__ __forceinline__ unsigned cvt_pk_bf16(float lo, float hi) { unsigned r; asm volatile("v_cvt_pk_bf16_f32 %0, %1, %2" : "=v"(r) : "v"(lo), "v"(hi)); return r; }
; #define PG8_BAR __builtin_amdgcn_s_barrier()
;     __device__ __forceinline__ static float sg(float g, float uu) { return g * __builtin_amdgcn_rcpf(1.0f + __builtin_amdgcn_exp2f(-1.4426950408889634f * g)) * uu; }
; template <class Epi, class Sched, bool ALIGN_EPI = false, bool SP2 = false>
; __device__ __forceinline__ void gemm_phase(PG8_LAS unsigned char* lds, const Gemm g, const Sched& S, const Epi& E) {
;     ...
;         if constexpr (ALIGN_EPI) { if (wr == 0) PG8_BAR; }
;         if constexpr (!Epi::AFTER_DRAIN) { E(acc, cur, wr, wc, fr, fq); S.done(cur); }
;         if (!has_next) break;
; #pragma unroll
;         for (int a = 0; a < 2; ++a)
; #pragma unroll
;             for (int b = 0; b < 2; ++b)
; #pragma unroll
;                 for (int m = 0; m < 4; ++m)
; #pragma unroll
;                     for (int n = 0; n < 2; ++n) acc[a][b][m][n] = (f32x4){0.f, 0.f, 0.f, 0.f};
;         cur = nxt; cA = nA; cB = nB; ++ui;
;         if constexpr (ALIGN_EPI) { if (wr == 1) PG8_BAR; }
;     __device__ __forceinline__ void operator()(const f32x4 (&acc)[2][2][4][2], const Unit& u, int wr, int wc, int fr, int fq) const {
;     ...
;         for (int ai = 0; ai < 2; ++ai)
; #pragma unroll
;             for (int m = 0; m < 4; ++m) {
;                 const int row = row0 + ai * HALF + m * 16;
;                 const float rs = rsv[ai][m];
;                 bf16_t* rowp = H + (size_t)row * ldh + (col0 >> 1);
; #pragma unroll
;                 for (int bj = 0; bj < 2; ++bj) {
;                     const f32x4 v0 = acc[ai][bj][m][0] * rs, v1 = acc[ai][bj][m][1] * rs;
;                     u32x2 w; w.x = cvt_pk_bf16(sg(v0[0], v0[1]), sg(v0[2], v0[3])); w.y = cvt_pk_bf16(sg(v1[0], v1[1]), sg(v1[2], v1[3]));
;                     *(u32x2*)(rowp + bj * (HALF / 2)) = w;
;                 }
;             }
	v_lshl_add_u64 v[34:35], v[34:35], 0, v[156:157]
	v_mul_f32_e32 v30, v30, v36
	v_mul_f32_e32 v30, v31, v30
	v_mul_f32_e32 v31, 0xbfb8aa3b, v32
	v_exp_f32_e32 v31, v31
	s_nop 0
	v_add_f32_e32 v31, 1.0, v31
	v_rcp_f32_e32 v31, v31
	s_nop 0
	v_mul_f32_e32 v31, v32, v31
	v_mul_f32_e32 v31, v33, v31
	v_cvt_pk_bf16_f32 v30, v30, v31
	v_mul_f32_e32 v31, 0xbfb8aa3b, v26
	v_exp_f32_e32 v31, v31
	s_nop 0
	v_add_f32_e32 v31, 1.0, v31
	v_rcp_f32_e32 v31, v31
	s_nop 0
	v_mul_f32_e32 v26, v26, v31
	v_mul_f32_e32 v26, v27, v26
	v_mul_f32_e32 v27, 0xbfb8aa3b, v28
	v_exp_f32_e32 v27, v27
	s_nop 0
	v_add_f32_e32 v27, 1.0, v27
	v_rcp_f32_e32 v27, v27
	s_nop 0
	v_mul_f32_e32 v27, v28, v27
	v_mul_f32_e32 v27, v29, v27
	v_cvt_pk_bf16_f32 v31, v26, v27
	v_mul_f32_e32 v26, 0xbfb8aa3b, v22
	v_exp_f32_e32 v26, v26
	global_store_dwordx2 v[34:35], v[30:31], off
	v_add_f32_e32 v26, 1.0, v26
	v_rcp_f32_e32 v26, v26
	s_nop 0
	v_mul_f32_e32 v22, v22, v26
	v_mul_f32_e32 v22, v23, v22
	v_mul_f32_e32 v23, 0xbfb8aa3b, v24
	v_exp_f32_e32 v23, v23
	s_nop 0
	v_add_f32_e32 v23, 1.0, v23
	v_rcp_f32_e32 v23, v23
	s_nop 0
	v_mul_f32_e32 v23, v24, v23
	v_mul_f32_e32 v23, v25, v23
	v_cvt_pk_bf16_f32 v22, v22, v23
	v_mul_f32_e32 v23, 0xbfb8aa3b, v18
	v_exp_f32_e32 v23, v23
	s_nop 0
	v_add_f32_e32 v23, 1.0, v23
	v_rcp_f32_e32 v23, v23
	s_nop 0
	v_mul_f32_e32 v18, v18, v23
	v_mul_f32_e32 v18, v19, v18
	v_mul_f32_e32 v19, 0xbfb8aa3b, v20
	v_exp_f32_e32 v19, v19
	s_nop 0
	v_add_f32_e32 v19, 1.0, v19
	v_rcp_f32_e32 v19, v19
	s_nop 0
	v_mul_f32_e32 v19, v20, v19
	v_mul_f32_e32 v20, 0xbfb8aa3b, v14
	v_exp_f32_e32 v20, v20
	v_mul_f32_e32 v19, v21, v19
	v_cvt_pk_bf16_f32 v23, v18, v19
	global_store_dwordx2 v[34:35], v[22:23], off offset:128
	v_add_f32_e32 v20, 1.0, v20
	v_rcp_f32_e32 v20, v20
	v_mad_i64_i32 v[18:19], s[30:31], v148, s96, v[132:133]
	v_lshl_add_u64 v[18:19], v[18:19], 0, v[156:157]
	v_mul_f32_e32 v14, v14, v20
	v_mul_f32_e32 v14, v15, v14
	v_mul_f32_e32 v15, 0xbfb8aa3b, v16
	v_exp_f32_e32 v15, v15
	s_mov_b64 s[30:31], -1
	v_add_f32_e32 v15, 1.0, v15
	v_rcp_f32_e32 v15, v15
	s_nop 0
	v_mul_f32_e32 v15, v16, v15
	v_mul_f32_e32 v15, v17, v15
	v_cvt_pk_bf16_f32 v14, v14, v15
	v_mul_f32_e32 v15, 0xbfb8aa3b, v10
	v_exp_f32_e32 v15, v15
	s_nop 0
	v_add_f32_e32 v15, 1.0, v15
	v_rcp_f32_e32 v15, v15
	s_nop 0
	v_mul_f32_e32 v10, v10, v15
	v_mul_f32_e32 v10, v11, v10
	v_mul_f32_e32 v11, 0xbfb8aa3b, v12
	v_exp_f32_e32 v11, v11
	s_nop 0
	v_add_f32_e32 v11, 1.0, v11
	v_rcp_f32_e32 v11, v11
	s_nop 0
	v_mul_f32_e32 v11, v12, v11
	v_mul_f32_e32 v11, v13, v11
	v_cvt_pk_bf16_f32 v15, v10, v11
	v_mul_f32_e32 v10, 0xbfb8aa3b, v6
	v_exp_f32_e32 v10, v10
	global_store_dwordx2 v[18:19], v[14:15], off
	v_add_f32_e32 v10, 1.0, v10
	v_rcp_f32_e32 v10, v10
	s_nop 0
	v_mul_f32_e32 v6, v6, v10
	v_mul_f32_e32 v6, v7, v6
	v_mul_f32_e32 v7, 0xbfb8aa3b, v8
	v_exp_f32_e32 v7, v7
	s_nop 0
	v_add_f32_e32 v7, 1.0, v7
	v_rcp_f32_e32 v7, v7
	s_nop 0
	v_mul_f32_e32 v7, v8, v7
	v_mul_f32_e32 v7, v9, v7
	v_cvt_pk_bf16_f32 v6, v6, v7
	v_mul_f32_e32 v7, 0xbfb8aa3b, v2
	v_exp_f32_e32 v7, v7
	s_nop 0
	v_add_f32_e32 v7, 1.0, v7
	v_rcp_f32_e32 v7, v7
	s_nop 0
	v_mul_f32_e32 v2, v2, v7
	v_mul_f32_e32 v2, v3, v2
	v_mul_f32_e32 v3, 0xbfb8aa3b, v4
	v_exp_f32_e32 v3, v3
	s_nop 0
	v_add_f32_e32 v3, 1.0, v3
	v_rcp_f32_e32 v3, v3
	s_nop 0
	v_mul_f32_e32 v3, v4, v3
	v_mul_f32_e32 v3, v5, v3
	v_cvt_pk_bf16_f32 v7, v2, v3
	global_store_dwordx2 v[18:19], v[6:7], off offset:128
	s_cbranch_vccnz .LBB0_3152
	s_andn2_b64 vcc, exec, s[20:21]
	s_cbranch_vccnz .LBB0_3151
	s_barrier
	s_branch .LBB0_3151

; __device__ __forceinline__ unsigned cvt_pk_bf16(float lo, float hi) { unsigned r; asm volatile("v_cvt_pk_bf16_f32 %0, %1, %2" : "=v"(r) : "v"(lo), "v"(hi)); return r; }
; __device__ __forceinline__ float row_rstd16_coop(const float* ssq, int row, int fq, float inv_n) {
;     const f32x4 a = *(const f32x4*)(ssq + (size_t)row * 16 + fq * 4);
;     float s = (a[0] + a[1]) + (a[2] + a[3]);
;     s += __shfl_xor(s, 16); s += __shfl_xor(s, 32);
;     return __builtin_amdgcn_rsqf(s * inv_n + EPS);
;     __device__ __forceinline__ void operator()(const f32x4 (&acc)[2][2][4][2], const Unit& u, int wr, int wc, int fr, int fq) const {
;         const int row0 = u.pm * BM + wr * 64 + fr, col0 = u.pn * BM + wc * 32 + 8 * fq;
;         float rsv[2][4];
; #pragma unroll
;         for (int ai = 0; ai < 2; ++ai) {
; #pragma unroll
;             for (int m = 0; m < 4; ++m) rsv[ai][m] = ssq ? row_rstd16_coop(ssq, row0 + ai * HALF + m * 16, fq, 1.0f / 1024.0f) : 1.0f;
;         }
; #pragma unroll
;         for (int ai = 0; ai < 2; ++ai)
; #pragma unroll
;             for (int m = 0; m < 4; ++m) {
;                 const int row = row0 + ai * HALF + m * 16;
;                 const float rs = rsv[ai][m];
;                 bf16_t* rowp = O + (size_t)row * ldc + col0;
; #pragma unroll
;                 for (int bj = 0; bj < 2; ++bj) {
;                     const f32x4 v0 = acc[ai][bj][m][0] * rs, v1 = acc[ai][bj][m][1] * rs;
;                     u32x4 w; w.x = cvt_pk_bf16(v0[0], v0[1]); w.y = cvt_pk_bf16(v0[2], v0[3]); w.z = cvt_pk_bf16(v1[0], v1[1]); w.w = cvt_pk_bf16(v1[2], v1[3]);
;                     *(u32x4*)(rowp + bj * HALF) = w;
.LBB0_3349:
	v_lshl_add_u32 v162, s55, 8, v1
	v_ashrrev_i32_e32 v163, 31, v162
	v_lshlrev_b64 v[130:131], 6, v[162:163]
	v_lshl_add_u64 v[130:131], v[142:143], 0, v[130:131]
	global_load_dwordx4 v[180:183], v[130:131], off offset:1024
	global_load_dwordx4 v[184:187], v[130:131], off offset:2048
	global_load_dwordx4 v[188:191], v[130:131], off offset:3072
	v_add_co_u32_e32 v208, vcc, 0x2000, v130
	s_nop 1
	v_addc_co_u32_e32 v209, vcc, 0, v131, vcc
	global_load_dwordx4 v[192:195], v[208:209], off
	global_load_dwordx4 v[196:199], v[208:209], off offset:1024
	global_load_dwordx4 v[200:203], v[208:209], off offset:2048
	global_load_dwordx4 v[204:207], v[208:209], off offset:3072
	global_load_dwordx4 v[130:133], v[130:131], off
	v_or_b32_e32 v164, 16, v162
	v_ashrrev_i32_e32 v165, 31, v164
	v_or_b32_e32 v166, 32, v162
	v_ashrrev_i32_e32 v167, 31, v166
	v_or_b32_e32 v168, 48, v162
	v_ashrrev_i32_e32 v169, 31, v168
	v_add_u32_e32 v170, 0x80, v162
	v_ashrrev_i32_e32 v171, 31, v170
	v_add_u32_e32 v172, 0x90, v162
	v_ashrrev_i32_e32 v173, 31, v172
	v_add_u32_e32 v174, 0xa0, v162
	v_ashrrev_i32_e32 v175, 31, v174
	v_add_u32_e32 v176, 0xb0, v162
	v_ashrrev_i32_e32 v177, 31, v176
	v_mad_i64_i32 v[162:163], s[26:27], v162, s30, 0
	v_lshl_add_u64 v[162:163], v[162:163], 1, s[18:19]
	s_and_b64 vcc, exec, s[4:5]
	s_waitcnt vmcnt(0)
	v_mov_b32_e32 v154, v131
	v_mov_b32_e32 v155, v132
	v_mov_b32_e32 v131, v133
	v_pk_add_f32 v[130:131], v[154:155], v[130:131]
	s_nop 0
	v_add_f32_e32 v130, v130, v131
	v_mov_b32_e32 v131, v130
	s_nop 1
	v_permlane16_swap_b32 v131, v130
	s_waitcnt lgkmcnt(0)
	v_add_f32_e32 v130, v130, v131
	v_mov_b32_e32 v131, v130
	s_nop 1
	v_permlane32_swap_b32 v131, v130
	s_waitcnt lgkmcnt(0)
	v_add_f32_e32 v130, v130, v131
	v_fmamk_f32 v130, v130, 0x3a800000, v231
	v_rsq_f32_e32 v148, v130
	s_nop 1
	v_pk_mul_f32 v[128:129], v[128:129], v[148:149] op_sel_hi:[1,0]
	v_pk_mul_f32 v[126:127], v[126:127], v[148:149] op_sel_hi:[1,0]
	v_pk_mul_f32 v[120:121], v[120:121], v[148:149] op_sel_hi:[1,0]
	v_pk_mul_f32 v[118:119], v[118:119], v[148:149] op_sel_hi:[1,0]
	v_add_f32_e32 v130, v181, v180
	v_add_f32_e32 v131, v182, v183
	s_nop 0
	v_add_f32_e32 v130, v130, v131
	v_mov_b32_e32 v131, v130
	s_nop 1
	v_permlane16_swap_b32 v131, v130
	s_waitcnt lgkmcnt(0)
	v_add_f32_e32 v130, v130, v131
	v_mov_b32_e32 v131, v130
	s_nop 1
	v_permlane32_swap_b32 v131, v130
	s_waitcnt lgkmcnt(0)
	v_add_f32_e32 v130, v130, v131
	v_fmamk_f32 v130, v130, 0x3a800000, v231
	v_rsq_f32_e32 v150, v130
	s_nop 1
	v_pk_mul_f32 v[112:113], v[112:113], v[150:151] op_sel_hi:[1,0]
	v_pk_mul_f32 v[110:111], v[110:111], v[150:151] op_sel_hi:[1,0]
	v_pk_mul_f32 v[104:105], v[104:105], v[150:151] op_sel_hi:[1,0]
	v_pk_mul_f32 v[102:103], v[102:103], v[150:151] op_sel_hi:[1,0]
	v_add_f32_e32 v130, v185, v184
	v_add_f32_e32 v131, v186, v187
	s_nop 0
	v_add_f32_e32 v130, v130, v131
	v_mov_b32_e32 v131, v130
	s_nop 1
	v_permlane16_swap_b32 v131, v130
	s_waitcnt lgkmcnt(0)
	v_add_f32_e32 v130, v130, v131
	v_mov_b32_e32 v131, v130
	s_nop 1
	v_permlane32_swap_b32 v131, v130
	s_waitcnt lgkmcnt(0)
	v_add_f32_e32 v130, v130, v131
	v_fmamk_f32 v130, v130, 0x3a800000, v231
	v_rsq_f32_e32 v152, v130
	s_nop 1
	v_pk_mul_f32 v[96:97], v[96:97], v[152:153] op_sel_hi:[1,0]
	v_pk_mul_f32 v[94:95], v[94:95], v[152:153] op_sel_hi:[1,0]
	v_pk_mul_f32 v[88:89], v[88:89], v[152:153] op_sel_hi:[1,0]
	v_pk_mul_f32 v[86:87], v[86:87], v[152:153] op_sel_hi:[1,0]
	v_add_f32_e32 v130, v189, v188
	v_add_f32_e32 v131, v190, v191
	s_nop 0
	v_add_f32_e32 v130, v130, v131
	v_mov_b32_e32 v131, v130
	s_nop 1
	v_permlane16_swap_b32 v131, v130
	s_waitcnt lgkmcnt(0)
	v_add_f32_e32 v130, v130, v131
	v_mov_b32_e32 v131, v130
	s_nop 1
	v_permlane32_swap_b32 v131, v130
	s_waitcnt lgkmcnt(0)
	v_add_f32_e32 v130, v130, v131
	v_fmamk_f32 v130, v130, 0x3a800000, v231
	v_rsq_f32_e32 v154, v130
	s_nop 1
	v_pk_mul_f32 v[80:81], v[80:81], v[154:155] op_sel_hi:[1,0]
	v_pk_mul_f32 v[78:79], v[78:79], v[154:155] op_sel_hi:[1,0]
	v_pk_mul_f32 v[72:73], v[72:73], v[154:155] op_sel_hi:[1,0]
	v_pk_mul_f32 v[70:71], v[70:71], v[154:155] op_sel_hi:[1,0]
	v_add_f32_e32 v130, v193, v192
	v_add_f32_e32 v131, v194, v195
	s_nop 0
	v_add_f32_e32 v130, v130, v131
	v_mov_b32_e32 v131, v130
	s_nop 1
	v_permlane16_swap_b32 v131, v130
	s_waitcnt lgkmcnt(0)
	v_add_f32_e32 v130, v130, v131
	v_mov_b32_e32 v131, v130
	s_nop 1
	v_permlane32_swap_b32 v131, v130
	s_waitcnt lgkmcnt(0)
	v_add_f32_e32 v130, v130, v131
	v_fmamk_f32 v130, v130, 0x3a800000, v231
	v_rsq_f32_e32 v156, v130
	s_nop 1
	v_pk_mul_f32 v[64:65], v[64:65], v[156:157] op_sel_hi:[1,0]
	v_pk_mul_f32 v[62:63], v[62:63], v[156:157] op_sel_hi:[1,0]
	v_pk_mul_f32 v[56:57], v[56:57], v[156:157] op_sel_hi:[1,0]
	v_pk_mul_f32 v[54:55], v[54:55], v[156:157] op_sel_hi:[1,0]
	v_add_f32_e32 v130, v197, v196
	v_add_f32_e32 v131, v198, v199
	s_nop 0
	v_add_f32_e32 v130, v130, v131
	v_mov_b32_e32 v131, v130
	s_nop 1
	v_permlane16_swap_b32 v131, v130
	s_waitcnt lgkmcnt(0)
	v_add_f32_e32 v130, v130, v131
	v_mov_b32_e32 v131, v130
	s_nop 1
	v_permlane32_swap_b32 v131, v130
	s_waitcnt lgkmcnt(0)
	v_add_f32_e32 v130, v130, v131
	v_fmamk_f32 v130, v130, 0x3a800000, v231
	v_rsq_f32_e32 v158, v130
	s_nop 1
	v_pk_mul_f32 v[48:49], v[48:49], v[158:159] op_sel_hi:[1,0]
	v_pk_mul_f32 v[46:47], v[46:47], v[158:159] op_sel_hi:[1,0]
	v_pk_mul_f32 v[40:41], v[40:41], v[158:159] op_sel_hi:[1,0]
	v_pk_mul_f32 v[38:39], v[38:39], v[158:159] op_sel_hi:[1,0]
	v_add_f32_e32 v130, v201, v200
	v_add_f32_e32 v131, v202, v203
	s_nop 0
	v_add_f32_e32 v130, v130, v131
	v_mov_b32_e32 v131, v130
	s_nop 1
	v_permlane16_swap_b32 v131, v130
	s_waitcnt lgkmcnt(0)
; __device__ __forceinline__ unsigned cvt_pk_bf16(float lo, float hi) { unsigned r; asm volatile("v_cvt_pk_bf16_f32 %0, %1, %2" : "=v"(r) : "v"(lo), "v"(hi)); return r; }
; __device__ __forceinline__ float row_rstd16_coop(const float* ssq, int row, int fq, float inv_n) {
;     const f32x4 a = *(const f32x4*)(ssq + (size_t)row * 16 + fq * 4);
;     float s = (a[0] + a[1]) + (a[2] + a[3]);
;     s += __shfl_xor(s, 16); s += __shfl_xor(s, 32);
;     return __builtin_amdgcn_rsqf(s * inv_n + EPS);
;     __device__ __forceinline__ void operator()(const f32x4 (&acc)[2][2][4][2], const Unit& u, int wr, int wc, int fr, int fq) const {
;         const int row0 = u.pm * BM + wr * 64 + fr, col0 = u.pn * BM + wc * 32 + 8 * fq;
;         float rsv[2][4];
; #pragma unroll
;         for (int ai = 0; ai < 2; ++ai) {
; #pragma unroll
;             for (int m = 0; m < 4; ++m) rsv[ai][m] = ssq ? row_rstd16_coop(ssq, row0 + ai * HALF + m * 16, fq, 1.0f / 1024.0f) : 1.0f;
;         }
; #pragma unroll
;         for (int ai = 0; ai < 2; ++ai)
; #pragma unroll
;             for (int m = 0; m < 4; ++m) {
;                 const int row = row0 + ai * HALF + m * 16;
;                 const float rs = rsv[ai][m];
;                 bf16_t* rowp = O + (size_t)row * ldc + col0;
; #pragma unroll
;                 for (int bj = 0; bj < 2; ++bj) {
;                     const f32x4 v0 = acc[ai][bj][m][0] * rs, v1 = acc[ai][bj][m][1] * rs;
;                     u32x4 w; w.x = cvt_pk_bf16(v0[0], v0[1]); w.y = cvt_pk_bf16(v0[2], v0[3]); w.z = cvt_pk_bf16(v1[0], v1[1]); w.w = cvt_pk_bf16(v1[2], v1[3]);
;                     *(u32x4*)(rowp + bj * HALF) = w;
	v_add_f32_e32 v130, v130, v131
	v_mov_b32_e32 v131, v130
	s_nop 1
	v_permlane32_swap_b32 v131, v130
	s_waitcnt lgkmcnt(0)
	v_add_f32_e32 v130, v130, v131
	v_fmamk_f32 v130, v130, 0x3a800000, v231
	v_rsq_f32_e32 v160, v130
	s_nop 1
	v_mov_b32_e32 v130, v204
	v_mov_b32_e32 v131, v205
	v_mov_b32_e32 v132, v206
	v_mov_b32_e32 v133, v207
	v_pk_mul_f32 v[32:33], v[32:33], v[160:161] op_sel_hi:[1,0]
	v_pk_mul_f32 v[30:31], v[30:31], v[160:161] op_sel_hi:[1,0]
	v_pk_mul_f32 v[24:25], v[24:25], v[160:161] op_sel_hi:[1,0]
	v_pk_mul_f32 v[22:23], v[22:23], v[160:161] op_sel_hi:[1,0]
	s_waitcnt vmcnt(0)
	v_mov_b32_e32 v179, v132
	v_lshl_or_b32 v132, s54, 8, v151
	v_mov_b32_e32 v178, v131
	v_mov_b32_e32 v131, v133
	v_ashrrev_i32_e32 v133, 31, v132
	v_lshlrev_b64 v[132:133], 1, v[132:133]
	v_pk_add_f32 v[130:131], v[178:179], v[130:131]
	v_lshl_add_u64 v[162:163], v[162:163], 0, v[132:133]
	v_pk_mul_f32 v[178:179], v[124:125], v[148:149] op_sel_hi:[1,0]
	v_pk_mul_f32 v[124:125], v[122:123], v[148:149] op_sel_hi:[1,0]
	v_cvt_pk_bf16_f32 v122, v126, v127
	v_cvt_pk_bf16_f32 v123, v128, v129
	v_add_f32_e32 v130, v130, v131
	v_cvt_pk_bf16_f32 v124, v124, v125
	v_cvt_pk_bf16_f32 v125, v178, v179
	global_store_dwordx4 v[162:163], v[122:125], off
	v_mov_b32_e32 v131, v130
	s_nop 1
	v_permlane16_swap_b32 v131, v130
	s_waitcnt lgkmcnt(0)
	v_add_f32_e32 v130, v130, v131
	v_pk_mul_f32 v[122:123], v[116:117], v[148:149] op_sel_hi:[1,0]
	v_pk_mul_f32 v[116:117], v[114:115], v[148:149] op_sel_hi:[1,0]
	v_cvt_pk_bf16_f32 v114, v118, v119
	v_cvt_pk_bf16_f32 v115, v120, v121
	v_mov_b32_e32 v131, v130
	s_nop 1
	v_permlane32_swap_b32 v131, v130
	v_cvt_pk_bf16_f32 v116, v116, v117
	v_cvt_pk_bf16_f32 v117, v122, v123
	global_store_dwordx4 v[162:163], v[114:117], off offset:256
	s_waitcnt lgkmcnt(0)
; __device__ __forceinline__ unsigned cvt_pk_bf16(float lo, float hi) { unsigned r; asm volatile("v_cvt_pk_bf16_f32 %0, %1, %2" : "=v"(r) : "v"(lo), "v"(hi)); return r; }
; #define PG8_BAR __builtin_amdgcn_s_barrier()
; template <class Epi, class Sched, bool ALIGN_EPI = false, bool SP2 = false>
; __device__ __forceinline__ void gemm_phase(PG8_LAS unsigned char* lds, const Gemm g, const Sched& S, const Epi& E) {
;     ...
;         if constexpr (ALIGN_EPI) { if (wr == 0) PG8_BAR; }
;         if constexpr (!Epi::AFTER_DRAIN) { E(acc, cur, wr, wc, fr, fq); S.done(cur); }
;         if (!has_next) break;
; #pragma unroll
;         for (int a = 0; a < 2; ++a)
; #pragma unroll
;             for (int b = 0; b < 2; ++b)
; #pragma unroll
;                 for (int m = 0; m < 4; ++m)
; #pragma unroll
;                     for (int n = 0; n < 2; ++n) acc[a][b][m][n] = (f32x4){0.f, 0.f, 0.f, 0.f};
;         cur = nxt; cA = nA; cB = nB; ++ui;
;         if constexpr (ALIGN_EPI) { if (wr == 1) PG8_BAR; }
;     __device__ __forceinline__ void operator()(const f32x4 (&acc)[2][2][4][2], const Unit& u, int wr, int wc, int fr, int fq) const {
;     ...
;         for (int ai = 0; ai < 2; ++ai)
; #pragma unroll
;             for (int m = 0; m < 4; ++m) {
;                 const int row = row0 + ai * HALF + m * 16;
;                 const float rs = rsv[ai][m];
;                 bf16_t* rowp = O + (size_t)row * ldc + col0;
; #pragma unroll
;                 for (int bj = 0; bj < 2; ++bj) {
;                     const f32x4 v0 = acc[ai][bj][m][0] * rs, v1 = acc[ai][bj][m][1] * rs;
;                     u32x4 w; w.x = cvt_pk_bf16(v0[0], v0[1]); w.y = cvt_pk_bf16(v0[2], v0[3]); w.z = cvt_pk_bf16(v1[0], v1[1]); w.w = cvt_pk_bf16(v1[2], v1[3]);
;                     *(u32x4*)(rowp + bj * HALF) = w;
;                 }
	v_add_f32_e32 v130, v130, v131
	v_mad_i64_i32 v[114:115], s[26:27], v164, s30, 0
	v_lshl_add_u64 v[114:115], v[114:115], 1, s[18:19]
	v_lshl_add_u64 v[114:115], v[114:115], 0, v[132:133]
	v_pk_mul_f32 v[116:117], v[108:109], v[150:151] op_sel_hi:[1,0]
	v_pk_mul_f32 v[108:109], v[106:107], v[150:151] op_sel_hi:[1,0]
	v_cvt_pk_bf16_f32 v106, v110, v111
	v_cvt_pk_bf16_f32 v107, v112, v113
	v_fmamk_f32 v130, v130, 0x3a800000, v231
	v_cvt_pk_bf16_f32 v108, v108, v109
	v_cvt_pk_bf16_f32 v109, v116, v117
	global_store_dwordx4 v[114:115], v[106:109], off
	v_rsq_f32_e32 v130, v130
	s_nop 0
	v_pk_mul_f32 v[106:107], v[100:101], v[150:151] op_sel_hi:[1,0]
	v_pk_mul_f32 v[100:101], v[98:99], v[150:151] op_sel_hi:[1,0]
	v_cvt_pk_bf16_f32 v98, v102, v103
	v_cvt_pk_bf16_f32 v99, v104, v105
	v_pk_mul_f32 v[16:17], v[16:17], v[130:131] op_sel_hi:[1,0]
	v_cvt_pk_bf16_f32 v100, v100, v101
	v_cvt_pk_bf16_f32 v101, v106, v107
	global_store_dwordx4 v[114:115], v[98:101], off offset:256
	v_pk_mul_f32 v[14:15], v[14:15], v[130:131] op_sel_hi:[1,0]
	v_pk_mul_f32 v[8:9], v[8:9], v[130:131] op_sel_hi:[1,0]
	v_mad_i64_i32 v[98:99], s[26:27], v166, s30, 0
	v_lshl_add_u64 v[98:99], v[98:99], 1, s[18:19]
	v_lshl_add_u64 v[98:99], v[98:99], 0, v[132:133]
	v_pk_mul_f32 v[100:101], v[92:93], v[152:153] op_sel_hi:[1,0]
	v_pk_mul_f32 v[92:93], v[90:91], v[152:153] op_sel_hi:[1,0]
	v_cvt_pk_bf16_f32 v90, v94, v95
	v_cvt_pk_bf16_f32 v91, v96, v97
	v_pk_mul_f32 v[6:7], v[6:7], v[130:131] op_sel_hi:[1,0]
	v_cvt_pk_bf16_f32 v92, v92, v93
	v_cvt_pk_bf16_f32 v93, v100, v101
	global_store_dwordx4 v[98:99], v[90:93], off
	s_nop 1
	v_pk_mul_f32 v[90:91], v[84:85], v[152:153] op_sel_hi:[1,0]
	v_pk_mul_f32 v[84:85], v[82:83], v[152:153] op_sel_hi:[1,0]
	v_cvt_pk_bf16_f32 v82, v86, v87
	v_cvt_pk_bf16_f32 v83, v88, v89
	s_nop 0
	v_cvt_pk_bf16_f32 v84, v84, v85
	v_cvt_pk_bf16_f32 v85, v90, v91
	global_store_dwordx4 v[98:99], v[82:85], off offset:256
	s_nop 1
	v_mad_i64_i32 v[82:83], s[26:27], v168, s30, 0
	v_lshl_add_u64 v[82:83], v[82:83], 1, s[18:19]
	v_lshl_add_u64 v[82:83], v[82:83], 0, v[132:133]
	v_pk_mul_f32 v[84:85], v[76:77], v[154:155] op_sel_hi:[1,0]
	v_pk_mul_f32 v[76:77], v[74:75], v[154:155] op_sel_hi:[1,0]
	v_cvt_pk_bf16_f32 v74, v78, v79
	v_cvt_pk_bf16_f32 v75, v80, v81
	s_nop 0
	v_cvt_pk_bf16_f32 v76, v76, v77
	v_cvt_pk_bf16_f32 v77, v84, v85
	global_store_dwordx4 v[82:83], v[74:77], off
	s_nop 1
	v_pk_mul_f32 v[74:75], v[68:69], v[154:155] op_sel_hi:[1,0]
	v_pk_mul_f32 v[68:69], v[66:67], v[154:155] op_sel_hi:[1,0]
	v_cvt_pk_bf16_f32 v66, v70, v71
	v_cvt_pk_bf16_f32 v67, v72, v73
	s_nop 0
	v_cvt_pk_bf16_f32 v68, v68, v69
	v_cvt_pk_bf16_f32 v69, v74, v75
	global_store_dwordx4 v[82:83], v[66:69], off offset:256
	s_nop 1
	v_mad_i64_i32 v[66:67], s[26:27], v170, s30, 0
	v_lshl_add_u64 v[66:67], v[66:67], 1, s[18:19]
	v_lshl_add_u64 v[66:67], v[66:67], 0, v[132:133]
	v_pk_mul_f32 v[68:69], v[60:61], v[156:157] op_sel_hi:[1,0]
	v_pk_mul_f32 v[60:61], v[58:59], v[156:157] op_sel_hi:[1,0]
	v_cvt_pk_bf16_f32 v58, v62, v63
	v_cvt_pk_bf16_f32 v59, v64, v65
	s_nop 0
	v_cvt_pk_bf16_f32 v60, v60, v61
	v_cvt_pk_bf16_f32 v61, v68, v69
	global_store_dwordx4 v[66:67], v[58:61], off
	s_nop 1
	v_pk_mul_f32 v[58:59], v[52:53], v[156:157] op_sel_hi:[1,0]
	v_pk_mul_f32 v[52:53], v[50:51], v[156:157] op_sel_hi:[1,0]
	v_cvt_pk_bf16_f32 v50, v54, v55
	v_cvt_pk_bf16_f32 v51, v56, v57
	s_nop 0
	v_cvt_pk_bf16_f32 v52, v52, v53
	v_cvt_pk_bf16_f32 v53, v58, v59
	global_store_dwordx4 v[66:67], v[50:53], off offset:256
	s_nop 1
	v_mad_i64_i32 v[50:51], s[26:27], v172, s30, 0
	v_lshl_add_u64 v[50:51], v[50:51], 1, s[18:19]
	v_lshl_add_u64 v[50:51], v[50:51], 0, v[132:133]
	v_pk_mul_f32 v[52:53], v[44:45], v[158:159] op_sel_hi:[1,0]
	v_pk_mul_f32 v[44:45], v[42:43], v[158:159] op_sel_hi:[1,0]
	v_cvt_pk_bf16_f32 v42, v46, v47
	v_cvt_pk_bf16_f32 v43, v48, v49
	s_nop 0
	v_cvt_pk_bf16_f32 v44, v44, v45
	v_cvt_pk_bf16_f32 v45, v52, v53
	global_store_dwordx4 v[50:51], v[42:45], off
	s_nop 1
	v_pk_mul_f32 v[42:43], v[36:37], v[158:159] op_sel_hi:[1,0]
	v_pk_mul_f32 v[36:37], v[34:35], v[158:159] op_sel_hi:[1,0]
	v_cvt_pk_bf16_f32 v34, v38, v39
	v_cvt_pk_bf16_f32 v35, v40, v41
	s_nop 0
	v_cvt_pk_bf16_f32 v36, v36, v37
	v_cvt_pk_bf16_f32 v37, v42, v43
	global_store_dwordx4 v[50:51], v[34:37], off offset:256
	s_nop 1
	v_mad_i64_i32 v[34:35], s[26:27], v174, s30, 0
	v_lshl_add_u64 v[34:35], v[34:35], 1, s[18:19]
	v_lshl_add_u64 v[34:35], v[34:35], 0, v[132:133]
	v_pk_mul_f32 v[36:37], v[28:29], v[160:161] op_sel_hi:[1,0]
	v_pk_mul_f32 v[28:29], v[26:27], v[160:161] op_sel_hi:[1,0]
	v_cvt_pk_bf16_f32 v26, v30, v31
	v_cvt_pk_bf16_f32 v27, v32, v33
	s_nop 0
	v_cvt_pk_bf16_f32 v28, v28, v29
	v_cvt_pk_bf16_f32 v29, v36, v37
	global_store_dwordx4 v[34:35], v[26:29], off
	s_nop 1
	v_pk_mul_f32 v[26:27], v[20:21], v[160:161] op_sel_hi:[1,0]
	v_pk_mul_f32 v[20:21], v[18:19], v[160:161] op_sel_hi:[1,0]
	v_cvt_pk_bf16_f32 v18, v22, v23
	v_cvt_pk_bf16_f32 v19, v24, v25
	s_nop 0
	v_cvt_pk_bf16_f32 v20, v20, v21
	v_cvt_pk_bf16_f32 v21, v26, v27
	global_store_dwordx4 v[34:35], v[18:21], off offset:256
	s_nop 1
	v_mad_i64_i32 v[18:19], s[26:27], v176, s30, 0
	v_lshl_add_u64 v[18:19], v[18:19], 1, s[18:19]
	v_lshl_add_u64 v[18:19], v[18:19], 0, v[132:133]
	v_pk_mul_f32 v[20:21], v[12:13], v[130:131] op_sel_hi:[1,0]
	v_pk_mul_f32 v[12:13], v[10:11], v[130:131] op_sel_hi:[1,0]
	v_cvt_pk_bf16_f32 v10, v14, v15
	v_cvt_pk_bf16_f32 v11, v16, v17
	s_mov_b64 s[26:27], -1
	v_cvt_pk_bf16_f32 v12, v12, v13
	v_cvt_pk_bf16_f32 v13, v20, v21
	global_store_dwordx4 v[18:19], v[10:13], off
	s_nop 1
	v_pk_mul_f32 v[10:11], v[4:5], v[130:131] op_sel_hi:[1,0]
	v_pk_mul_f32 v[4:5], v[2:3], v[130:131] op_sel_hi:[1,0]
	v_cvt_pk_bf16_f32 v2, v6, v7
	v_cvt_pk_bf16_f32 v3, v8, v9
	s_nop 0
	v_cvt_pk_bf16_f32 v4, v4, v5
	v_cvt_pk_bf16_f32 v5, v10, v11
	global_store_dwordx4 v[18:19], v[2:5], off offset:256
	s_cbranch_vccnz .LBB0_3333
	s_andn2_b64 vcc, exec, s[16:17]
	s_cbranch_vccnz .LBB0_3332
	s_barrier
	s_branch .LBB0_3332

; __device__ __forceinline__ float row_rstd16_coop(const float* ssq, int row, int fq, float inv_n) {
;     const f32x4 a = *(const f32x4*)(ssq + (size_t)row * 16 + fq * 4);
;     float s = (a[0] + a[1]) + (a[2] + a[3]);
;     s += __shfl_xor(s, 16); s += __shfl_xor(s, 32);
;     return __builtin_amdgcn_rsqf(s * inv_n + EPS);
; }
;     __device__ __forceinline__ void operator()(const f32x4 (&acc)[2][2][4][2], const Unit& u, int wr, int wc, int fr, int fq) const {
;         const int row0 = u.pm * BM + wr * 64 + fr, col0 = u.pn * BM + wc * 32 + 8 * fq;
;         float rsv[2][4];
; #pragma unroll
;         for (int ai = 0; ai < 2; ++ai) {
; #pragma unroll
;             for (int m = 0; m < 4; ++m) rsv[ai][m] = ssq ? row_rstd16_coop(ssq, row0 + ai * HALF + m * 16, fq, 1.0f / 1024.0f) : 1.0f;
;         }
; #pragma unroll
;         for (int ai = 0; ai < 2; ++ai)
; #pragma unroll
;             for (int m = 0; m < 4; ++m) {
;                 const int row = row0 + ai * HALF + m * 16;
;                 const float rs = rsv[ai][m];
;                 bf16_t* rowp = O + (size_t)row * ldc + col0;
; #pragma unroll
;                 for (int bj = 0; bj < 2; ++bj) {
;                     const f32x4 v0 = acc[ai][bj][m][0] * rs, v1 = acc[ai][bj][m][1] * rs;
.LBB0_4583:
	v_lshl_add_u32 v160, s52, 8, v1
	v_ashrrev_i32_e32 v161, 31, v160
	v_lshlrev_b64 v[130:131], 6, v[160:161]
	v_lshl_add_u64 v[130:131], v[142:143], 0, v[130:131]
	global_load_dwordx4 v[180:183], v[130:131], off offset:1024
	global_load_dwordx4 v[184:187], v[130:131], off offset:2048
	global_load_dwordx4 v[188:191], v[130:131], off offset:3072
	v_add_co_u32_e32 v208, vcc, 0x2000, v130
	s_nop 1
	v_addc_co_u32_e32 v209, vcc, 0, v131, vcc
	global_load_dwordx4 v[192:195], v[208:209], off
	global_load_dwordx4 v[196:199], v[208:209], off offset:1024
	global_load_dwordx4 v[200:203], v[208:209], off offset:2048
	global_load_dwordx4 v[204:207], v[208:209], off offset:3072
	global_load_dwordx4 v[130:133], v[130:131], off
	v_or_b32_e32 v164, 16, v160
	v_ashrrev_i32_e32 v165, 31, v164
	v_or_b32_e32 v166, 32, v160
	v_ashrrev_i32_e32 v167, 31, v166
	v_or_b32_e32 v168, 48, v160
	v_ashrrev_i32_e32 v169, 31, v168
	v_add_u32_e32 v170, 0x80, v160
	v_ashrrev_i32_e32 v171, 31, v170
	v_add_u32_e32 v172, 0x90, v160
	v_ashrrev_i32_e32 v173, 31, v172
	v_add_u32_e32 v174, 0xa0, v160
	v_ashrrev_i32_e32 v175, 31, v174
	v_add_u32_e32 v176, 0xb0, v160
	v_ashrrev_i32_e32 v177, 31, v176
	v_lshlrev_b64 v[160:161], 11, v[160:161]
	v_lshl_add_u64 v[160:161], s[16:17], 0, v[160:161]
	s_mov_b64 s[24:25], -1
	s_and_b64 vcc, exec, s[4:5]
	s_waitcnt vmcnt(0)
	v_mov_b32_e32 v154, v131
	v_mov_b32_e32 v155, v132
	v_mov_b32_e32 v131, v133
	v_pk_add_f32 v[130:131], v[154:155], v[130:131]
	s_nop 0
	v_add_f32_e32 v130, v130, v131
	v_mov_b32_e32 v131, v130
	s_nop 1
	v_permlane16_swap_b32 v131, v130
	s_waitcnt lgkmcnt(0)
	v_add_f32_e32 v130, v130, v131
	v_mov_b32_e32 v131, v130
	s_nop 1
	v_permlane32_swap_b32 v131, v130
	s_waitcnt lgkmcnt(0)
	v_add_f32_e32 v130, v130, v131
	v_fmamk_f32 v130, v130, 0x3a800000, v231
	v_rsq_f32_e32 v148, v130
	s_nop 1
	v_pk_mul_f32 v[128:129], v[128:129], v[148:149] op_sel_hi:[1,0]
	v_pk_mul_f32 v[126:127], v[126:127], v[148:149] op_sel_hi:[1,0]
	v_pk_mul_f32 v[120:121], v[120:121], v[148:149] op_sel_hi:[1,0]
	v_pk_mul_f32 v[118:119], v[118:119], v[148:149] op_sel_hi:[1,0]
	v_add_f32_e32 v130, v181, v180
	v_add_f32_e32 v131, v182, v183
	s_nop 0
	v_add_f32_e32 v130, v130, v131
	v_mov_b32_e32 v131, v130
	s_nop 1
	v_permlane16_swap_b32 v131, v130
	s_waitcnt lgkmcnt(0)
	v_add_f32_e32 v130, v130, v131
	v_mov_b32_e32 v131, v130
	s_nop 1
	v_permlane32_swap_b32 v131, v130
	s_waitcnt lgkmcnt(0)
	v_add_f32_e32 v130, v130, v131
	v_fmamk_f32 v130, v130, 0x3a800000, v231
	v_rsq_f32_e32 v150, v130
	s_nop 1
	v_pk_mul_f32 v[112:113], v[112:113], v[150:151] op_sel_hi:[1,0]
	v_pk_mul_f32 v[110:111], v[110:111], v[150:151] op_sel_hi:[1,0]
	v_pk_mul_f32 v[104:105], v[104:105], v[150:151] op_sel_hi:[1,0]
	v_pk_mul_f32 v[102:103], v[102:103], v[150:151] op_sel_hi:[1,0]
	v_add_f32_e32 v130, v185, v184
	v_add_f32_e32 v131, v186, v187
	s_nop 0
	v_add_f32_e32 v130, v130, v131
	v_mov_b32_e32 v131, v130
	s_nop 1
	v_permlane16_swap_b32 v131, v130
	s_waitcnt lgkmcnt(0)
	v_add_f32_e32 v130, v130, v131
	v_mov_b32_e32 v131, v130
	s_nop 1
	v_permlane32_swap_b32 v131, v130
	s_waitcnt lgkmcnt(0)
	v_add_f32_e32 v130, v130, v131
	v_fmamk_f32 v130, v130, 0x3a800000, v231
	v_rsq_f32_e32 v152, v130
	s_nop 1
	v_pk_mul_f32 v[96:97], v[96:97], v[152:153] op_sel_hi:[1,0]
	v_pk_mul_f32 v[94:95], v[94:95], v[152:153] op_sel_hi:[1,0]
	v_pk_mul_f32 v[88:89], v[88:89], v[152:153] op_sel_hi:[1,0]
	v_pk_mul_f32 v[86:87], v[86:87], v[152:153] op_sel_hi:[1,0]
	v_add_f32_e32 v130, v189, v188
	v_add_f32_e32 v131, v190, v191
	s_nop 0
	v_add_f32_e32 v130, v130, v131
	v_mov_b32_e32 v131, v130
	s_nop 1
	v_permlane16_swap_b32 v131, v130
	s_waitcnt lgkmcnt(0)
	v_add_f32_e32 v130, v130, v131
	v_mov_b32_e32 v131, v130
	s_nop 1
	v_permlane32_swap_b32 v131, v130
	s_waitcnt lgkmcnt(0)
	v_add_f32_e32 v130, v130, v131
	v_fmamk_f32 v130, v130, 0x3a800000, v231
	v_rsq_f32_e32 v154, v130
	s_nop 1
	v_pk_mul_f32 v[80:81], v[80:81], v[154:155] op_sel_hi:[1,0]
	v_pk_mul_f32 v[78:79], v[78:79], v[154:155] op_sel_hi:[1,0]
	v_pk_mul_f32 v[72:73], v[72:73], v[154:155] op_sel_hi:[1,0]
	v_pk_mul_f32 v[70:71], v[70:71], v[154:155] op_sel_hi:[1,0]
	v_add_f32_e32 v130, v193, v192
	v_add_f32_e32 v131, v194, v195
	s_nop 0
	v_add_f32_e32 v130, v130, v131
	v_mov_b32_e32 v131, v130
	s_nop 1
	v_permlane16_swap_b32 v131, v130
	s_waitcnt lgkmcnt(0)
	v_add_f32_e32 v130, v130, v131
	v_mov_b32_e32 v131, v130
	s_nop 1
	v_permlane32_swap_b32 v131, v130
	s_waitcnt lgkmcnt(0)
	v_add_f32_e32 v130, v130, v131
	v_fmamk_f32 v130, v130, 0x3a800000, v231
	v_rsq_f32_e32 v156, v130
	s_nop 1
	v_pk_mul_f32 v[64:65], v[64:65], v[156:157] op_sel_hi:[1,0]
	v_pk_mul_f32 v[62:63], v[62:63], v[156:157] op_sel_hi:[1,0]
	v_pk_mul_f32 v[56:57], v[56:57], v[156:157] op_sel_hi:[1,0]
	v_pk_mul_f32 v[54:55], v[54:55], v[156:157] op_sel_hi:[1,0]
	v_add_f32_e32 v130, v197, v196
	v_add_f32_e32 v131, v198, v199
	s_nop 0
	v_add_f32_e32 v130, v130, v131
	v_mov_b32_e32 v131, v130
	s_nop 1
	v_permlane16_swap_b32 v131, v130
	s_waitcnt lgkmcnt(0)
	v_add_f32_e32 v130, v130, v131
	v_mov_b32_e32 v131, v130
	s_nop 1
	v_permlane32_swap_b32 v131, v130
	s_waitcnt lgkmcnt(0)
	v_add_f32_e32 v130, v130, v131
	v_fmamk_f32 v130, v130, 0x3a800000, v231
	v_rsq_f32_e32 v158, v130
	s_nop 1
	v_pk_mul_f32 v[48:49], v[48:49], v[158:159] op_sel_hi:[1,0]
	v_pk_mul_f32 v[46:47], v[46:47], v[158:159] op_sel_hi:[1,0]
	v_pk_mul_f32 v[40:41], v[40:41], v[158:159] op_sel_hi:[1,0]
	v_pk_mul_f32 v[38:39], v[38:39], v[158:159] op_sel_hi:[1,0]
	v_add_f32_e32 v130, v201, v200
	v_add_f32_e32 v131, v202, v203
	s_nop 0
	v_add_f32_e32 v130, v130, v131
	v_mov_b32_e32 v131, v130
	s_nop 1
	v_permlane16_swap_b32 v131, v130
	s_waitcnt lgkmcnt(0)
; __device__ __forceinline__ unsigned cvt_pk_bf16(float lo, float hi) { unsigned r; asm volatile("v_cvt_pk_bf16_f32 %0, %1, %2" : "=v"(r) : "v"(lo), "v"(hi)); return r; }
; __device__ __forceinline__ float row_rstd16_coop(const float* ssq, int row, int fq, float inv_n) {
;     const f32x4 a = *(const f32x4*)(ssq + (size_t)row * 16 + fq * 4);
;     float s = (a[0] + a[1]) + (a[2] + a[3]);
;     s += __shfl_xor(s, 16); s += __shfl_xor(s, 32);
;     return __builtin_amdgcn_rsqf(s * inv_n + EPS);
; }
;     __device__ __forceinline__ void operator()(const f32x4 (&acc)[2][2][4][2], const Unit& u, int wr, int wc, int fr, int fq) const {
;     ...
;         for (int ai = 0; ai < 2; ++ai)
; #pragma unroll
;             for (int m = 0; m < 4; ++m) {
;                 const int row = row0 + ai * HALF + m * 16;
;                 const float rs = rsv[ai][m];
;                 bf16_t* rowp = O + (size_t)row * ldc + col0;
; #pragma unroll
;                 for (int bj = 0; bj < 2; ++bj) {
;                     const f32x4 v0 = acc[ai][bj][m][0] * rs, v1 = acc[ai][bj][m][1] * rs;
;                     u32x4 w; w.x = cvt_pk_bf16(v0[0], v0[1]); w.y = cvt_pk_bf16(v0[2], v0[3]); w.z = cvt_pk_bf16(v1[0], v1[1]); w.w = cvt_pk_bf16(v1[2], v1[3]);
;                     *(u32x4*)(rowp + bj * HALF) = w;
;                 }
	v_add_f32_e32 v130, v130, v131
	v_mov_b32_e32 v131, v130
	s_nop 1
	v_permlane32_swap_b32 v131, v130
	s_waitcnt lgkmcnt(0)
	v_add_f32_e32 v130, v130, v131
	v_fmamk_f32 v130, v130, 0x3a800000, v231
	v_rsq_f32_e32 v162, v130
	s_nop 1
	v_mov_b32_e32 v130, v204
	v_mov_b32_e32 v131, v205
	v_mov_b32_e32 v132, v206
	v_mov_b32_e32 v133, v207
	v_pk_mul_f32 v[32:33], v[32:33], v[162:163] op_sel_hi:[1,0]
	v_pk_mul_f32 v[30:31], v[30:31], v[162:163] op_sel_hi:[1,0]
	v_pk_mul_f32 v[24:25], v[24:25], v[162:163] op_sel_hi:[1,0]
	v_pk_mul_f32 v[22:23], v[22:23], v[162:163] op_sel_hi:[1,0]
	s_waitcnt vmcnt(0)
	v_mov_b32_e32 v179, v132
	v_lshl_or_b32 v132, s51, 8, v151
	v_mov_b32_e32 v178, v131
	v_mov_b32_e32 v131, v133
	v_ashrrev_i32_e32 v133, 31, v132
	v_lshlrev_b64 v[132:133], 1, v[132:133]
	v_pk_add_f32 v[130:131], v[178:179], v[130:131]
	v_lshl_add_u64 v[160:161], v[160:161], 0, v[132:133]
	v_pk_mul_f32 v[178:179], v[124:125], v[148:149] op_sel_hi:[1,0]
	v_pk_mul_f32 v[124:125], v[122:123], v[148:149] op_sel_hi:[1,0]
	v_cvt_pk_bf16_f32 v122, v126, v127
	v_cvt_pk_bf16_f32 v123, v128, v129
	v_add_f32_e32 v130, v130, v131
	v_cvt_pk_bf16_f32 v124, v124, v125
	v_cvt_pk_bf16_f32 v125, v178, v179
	global_store_dwordx4 v[160:161], v[122:125], off
	v_mov_b32_e32 v131, v130
	s_nop 1
	v_permlane16_swap_b32 v131, v130
	s_waitcnt lgkmcnt(0)
	v_add_f32_e32 v130, v130, v131
	v_pk_mul_f32 v[122:123], v[116:117], v[148:149] op_sel_hi:[1,0]
	v_pk_mul_f32 v[116:117], v[114:115], v[148:149] op_sel_hi:[1,0]
	v_cvt_pk_bf16_f32 v114, v118, v119
	v_cvt_pk_bf16_f32 v115, v120, v121
	v_mov_b32_e32 v131, v130
	s_nop 1
	v_permlane32_swap_b32 v131, v130
	v_cvt_pk_bf16_f32 v116, v116, v117
	v_cvt_pk_bf16_f32 v117, v122, v123
	global_store_dwordx4 v[160:161], v[114:117], off offset:256
	s_waitcnt lgkmcnt(0)
; __device__ __forceinline__ unsigned cvt_pk_bf16(float lo, float hi) { unsigned r; asm volatile("v_cvt_pk_bf16_f32 %0, %1, %2" : "=v"(r) : "v"(lo), "v"(hi)); return r; }
;     __device__ __forceinline__ void operator()(const f32x4 (&acc)[2][2][4][2], const Unit& u, int wr, int wc, int fr, int fq) const {
;     ...
;         for (int ai = 0; ai < 2; ++ai)
; #pragma unroll
;             for (int m = 0; m < 4; ++m) {
;                 const int row = row0 + ai * HALF + m * 16;
;                 const float rs = rsv[ai][m];
;                 bf16_t* rowp = O + (size_t)row * ldc + col0;
; #pragma unroll
;                 for (int bj = 0; bj < 2; ++bj) {
;                     const f32x4 v0 = acc[ai][bj][m][0] * rs, v1 = acc[ai][bj][m][1] * rs;
;                     u32x4 w; w.x = cvt_pk_bf16(v0[0], v0[1]); w.y = cvt_pk_bf16(v0[2], v0[3]); w.z = cvt_pk_bf16(v1[0], v1[1]); w.w = cvt_pk_bf16(v1[2], v1[3]);
;                     *(u32x4*)(rowp + bj * HALF) = w;
;                 }
	v_add_f32_e32 v130, v130, v131
	v_lshlrev_b64 v[114:115], 11, v[164:165]
	v_lshl_add_u64 v[114:115], s[16:17], 0, v[114:115]
	v_lshl_add_u64 v[114:115], v[114:115], 0, v[132:133]
	v_pk_mul_f32 v[116:117], v[108:109], v[150:151] op_sel_hi:[1,0]
	v_pk_mul_f32 v[108:109], v[106:107], v[150:151] op_sel_hi:[1,0]
	v_cvt_pk_bf16_f32 v106, v110, v111
	v_cvt_pk_bf16_f32 v107, v112, v113
	v_fmamk_f32 v130, v130, 0x3a800000, v231
	v_cvt_pk_bf16_f32 v108, v108, v109
	v_cvt_pk_bf16_f32 v109, v116, v117
	global_store_dwordx4 v[114:115], v[106:109], off
	v_rsq_f32_e32 v130, v130
	s_nop 0
	v_pk_mul_f32 v[106:107], v[100:101], v[150:151] op_sel_hi:[1,0]
	v_pk_mul_f32 v[100:101], v[98:99], v[150:151] op_sel_hi:[1,0]
	v_cvt_pk_bf16_f32 v98, v102, v103
	v_cvt_pk_bf16_f32 v99, v104, v105
	v_pk_mul_f32 v[16:17], v[16:17], v[130:131] op_sel_hi:[1,0]
	v_cvt_pk_bf16_f32 v100, v100, v101
	v_cvt_pk_bf16_f32 v101, v106, v107
	global_store_dwordx4 v[114:115], v[98:101], off offset:256
	v_pk_mul_f32 v[14:15], v[14:15], v[130:131] op_sel_hi:[1,0]
	v_pk_mul_f32 v[8:9], v[8:9], v[130:131] op_sel_hi:[1,0]
	v_lshlrev_b64 v[98:99], 11, v[166:167]
	v_lshl_add_u64 v[98:99], s[16:17], 0, v[98:99]
	v_lshl_add_u64 v[98:99], v[98:99], 0, v[132:133]
	v_pk_mul_f32 v[100:101], v[92:93], v[152:153] op_sel_hi:[1,0]
	v_pk_mul_f32 v[92:93], v[90:91], v[152:153] op_sel_hi:[1,0]
	v_cvt_pk_bf16_f32 v90, v94, v95
	v_cvt_pk_bf16_f32 v91, v96, v97
	v_pk_mul_f32 v[6:7], v[6:7], v[130:131] op_sel_hi:[1,0]
	v_cvt_pk_bf16_f32 v92, v92, v93
	v_cvt_pk_bf16_f32 v93, v100, v101
	global_store_dwordx4 v[98:99], v[90:93], off
	s_nop 1
	v_pk_mul_f32 v[90:91], v[84:85], v[152:153] op_sel_hi:[1,0]
	v_pk_mul_f32 v[84:85], v[82:83], v[152:153] op_sel_hi:[1,0]
	v_cvt_pk_bf16_f32 v82, v86, v87
	v_cvt_pk_bf16_f32 v83, v88, v89
	s_nop 0
	v_cvt_pk_bf16_f32 v84, v84, v85
	v_cvt_pk_bf16_f32 v85, v90, v91
	global_store_dwordx4 v[98:99], v[82:85], off offset:256
	s_nop 1
	v_lshlrev_b64 v[82:83], 11, v[168:169]
	v_lshl_add_u64 v[82:83], s[16:17], 0, v[82:83]
	v_lshl_add_u64 v[82:83], v[82:83], 0, v[132:133]
	v_pk_mul_f32 v[84:85], v[76:77], v[154:155] op_sel_hi:[1,0]
	v_pk_mul_f32 v[76:77], v[74:75], v[154:155] op_sel_hi:[1,0]
	v_cvt_pk_bf16_f32 v74, v78, v79
	v_cvt_pk_bf16_f32 v75, v80, v81
	s_nop 0
	v_cvt_pk_bf16_f32 v76, v76, v77
	v_cvt_pk_bf16_f32 v77, v84, v85
	global_store_dwordx4 v[82:83], v[74:77], off
	s_nop 1
	v_pk_mul_f32 v[74:75], v[68:69], v[154:155] op_sel_hi:[1,0]
	v_pk_mul_f32 v[68:69], v[66:67], v[154:155] op_sel_hi:[1,0]
	v_cvt_pk_bf16_f32 v66, v70, v71
	v_cvt_pk_bf16_f32 v67, v72, v73
	s_nop 0
	v_cvt_pk_bf16_f32 v68, v68, v69
	v_cvt_pk_bf16_f32 v69, v74, v75
	global_store_dwordx4 v[82:83], v[66:69], off offset:256
	s_nop 1
	v_lshlrev_b64 v[66:67], 11, v[170:171]
	v_lshl_add_u64 v[66:67], s[16:17], 0, v[66:67]
	v_lshl_add_u64 v[66:67], v[66:67], 0, v[132:133]
	v_pk_mul_f32 v[68:69], v[60:61], v[156:157] op_sel_hi:[1,0]
	v_pk_mul_f32 v[60:61], v[58:59], v[156:157] op_sel_hi:[1,0]
	v_cvt_pk_bf16_f32 v58, v62, v63
	v_cvt_pk_bf16_f32 v59, v64, v65
	s_nop 0
	v_cvt_pk_bf16_f32 v60, v60, v61
	v_cvt_pk_bf16_f32 v61, v68, v69
	global_store_dwordx4 v[66:67], v[58:61], off
	s_nop 1
	v_pk_mul_f32 v[58:59], v[52:53], v[156:157] op_sel_hi:[1,0]
	v_pk_mul_f32 v[52:53], v[50:51], v[156:157] op_sel_hi:[1,0]
	v_cvt_pk_bf16_f32 v50, v54, v55
	v_cvt_pk_bf16_f32 v51, v56, v57
	s_nop 0
	v_cvt_pk_bf16_f32 v52, v52, v53
	v_cvt_pk_bf16_f32 v53, v58, v59
	global_store_dwordx4 v[66:67], v[50:53], off offset:256
	s_nop 1
	v_lshlrev_b64 v[50:51], 11, v[172:173]
	v_lshl_add_u64 v[50:51], s[16:17], 0, v[50:51]
	v_lshl_add_u64 v[50:51], v[50:51], 0, v[132:133]
	v_pk_mul_f32 v[52:53], v[44:45], v[158:159] op_sel_hi:[1,0]
	v_pk_mul_f32 v[44:45], v[42:43], v[158:159] op_sel_hi:[1,0]
	v_cvt_pk_bf16_f32 v42, v46, v47
	v_cvt_pk_bf16_f32 v43, v48, v49
	s_nop 0
	v_cvt_pk_bf16_f32 v44, v44, v45
	v_cvt_pk_bf16_f32 v45, v52, v53
	global_store_dwordx4 v[50:51], v[42:45], off
	s_nop 1
	v_pk_mul_f32 v[42:43], v[36:37], v[158:159] op_sel_hi:[1,0]
	v_pk_mul_f32 v[36:37], v[34:35], v[158:159] op_sel_hi:[1,0]
	v_cvt_pk_bf16_f32 v34, v38, v39
	v_cvt_pk_bf16_f32 v35, v40, v41
	s_nop 0
	v_cvt_pk_bf16_f32 v36, v36, v37
	v_cvt_pk_bf16_f32 v37, v42, v43
	global_store_dwordx4 v[50:51], v[34:37], off offset:256
	s_nop 1
	v_lshlrev_b64 v[34:35], 11, v[174:175]
	v_lshl_add_u64 v[34:35], s[16:17], 0, v[34:35]
	v_lshl_add_u64 v[34:35], v[34:35], 0, v[132:133]
	v_pk_mul_f32 v[36:37], v[28:29], v[162:163] op_sel_hi:[1,0]
	v_pk_mul_f32 v[28:29], v[26:27], v[162:163] op_sel_hi:[1,0]
	v_cvt_pk_bf16_f32 v26, v30, v31
	v_cvt_pk_bf16_f32 v27, v32, v33
	s_nop 0
	v_cvt_pk_bf16_f32 v28, v28, v29
	v_cvt_pk_bf16_f32 v29, v36, v37
	global_store_dwordx4 v[34:35], v[26:29], off
	s_nop 1
	v_pk_mul_f32 v[26:27], v[20:21], v[162:163] op_sel_hi:[1,0]
	v_pk_mul_f32 v[20:21], v[18:19], v[162:163] op_sel_hi:[1,0]
	v_cvt_pk_bf16_f32 v18, v22, v23
	v_cvt_pk_bf16_f32 v19, v24, v25
	s_nop 0
	v_cvt_pk_bf16_f32 v20, v20, v21
	v_cvt_pk_bf16_f32 v21, v26, v27
	global_store_dwordx4 v[34:35], v[18:21], off offset:256
	s_nop 1
	v_lshlrev_b64 v[18:19], 11, v[176:177]
	v_lshl_add_u64 v[18:19], s[16:17], 0, v[18:19]
	v_lshl_add_u64 v[18:19], v[18:19], 0, v[132:133]
	v_pk_mul_f32 v[20:21], v[12:13], v[130:131] op_sel_hi:[1,0]
	v_pk_mul_f32 v[12:13], v[10:11], v[130:131] op_sel_hi:[1,0]
	v_cvt_pk_bf16_f32 v10, v14, v15
	v_cvt_pk_bf16_f32 v11, v16, v17
	s_nop 0
	v_cvt_pk_bf16_f32 v12, v12, v13
	v_cvt_pk_bf16_f32 v13, v20, v21
	global_store_dwordx4 v[18:19], v[10:13], off
	s_nop 1
	v_pk_mul_f32 v[10:11], v[4:5], v[130:131] op_sel_hi:[1,0]
	v_pk_mul_f32 v[4:5], v[2:3], v[130:131] op_sel_hi:[1,0]
	v_cvt_pk_bf16_f32 v2, v6, v7
	v_cvt_pk_bf16_f32 v3, v8, v9
	s_nop 0
	v_cvt_pk_bf16_f32 v4, v4, v5
	v_cvt_pk_bf16_f32 v5, v10, v11
	global_store_dwordx4 v[18:19], v[2:5], off offset:256
	s_cbranch_vccnz .LBB0_4567
	s_andn2_b64 vcc, exec, s[14:15]
	s_cbranch_vccnz .LBB0_4566
	s_barrier
	s_branch .LBB0_4566

; __device__ __forceinline__ float row_rstd16_coop(const float* ssq, int row, int fq, float inv_n) {
;     const f32x4 a = *(const f32x4*)(ssq + (size_t)row * 16 + fq * 4);
;     float s = (a[0] + a[1]) + (a[2] + a[3]);
;     s += __shfl_xor(s, 16); s += __shfl_xor(s, 32);
;     return __builtin_amdgcn_rsqf(s * inv_n + EPS);
; }
;     __device__ __forceinline__ void operator()(const f32x4 (&acc)[2][2][4][2], const Unit& u, int wr, int wc, int fr, int fq) const {
;     ...
;         for (int ai = 0; ai < 2; ++ai) {
; #pragma unroll
;             for (int m = 0; m < 4; ++m) rsv[ai][m] = row_rstd16_coop(ssq, row0 + ai * HALF + m * 16, fq, 1.0f / 1024.0f);
;         }
; #pragma unroll
;         for (int ai = 0; ai < 2; ++ai)
; #pragma unroll
;             for (int m = 0; m < 4; ++m) {
;                 const int row = row0 + ai * HALF + m * 16;
;                 const float rs = rsv[ai][m];
;                 bf16_t* rowp = H + (size_t)row * ldh + (col0 >> 1);
; #pragma unroll
;                 for (int bj = 0; bj < 2; ++bj) {
;                     const f32x4 v0 = acc[ai][bj][m][0] * rs, v1 = acc[ai][bj][m][1] * rs;
.LBB0_4848:
	v_lshl_add_u32 v156, s52, 8, v1
	v_ashrrev_i32_e32 v157, 31, v156
	v_lshlrev_b64 v[130:131], 6, v[156:157]
	v_lshl_add_u64 v[130:131], v[142:143], 0, v[130:131]
	global_load_dwordx4 v[182:185], v[130:131], off offset:1024
	global_load_dwordx4 v[186:189], v[130:131], off offset:2048
	global_load_dwordx4 v[190:193], v[130:131], off offset:3072
	v_add_co_u32_e32 v210, vcc, 0x2000, v130
	s_nop 1
	v_addc_co_u32_e32 v211, vcc, 0, v131, vcc
	global_load_dwordx4 v[194:197], v[210:211], off
	global_load_dwordx4 v[198:201], v[210:211], off offset:1024
	global_load_dwordx4 v[202:205], v[210:211], off offset:2048
	global_load_dwordx4 v[206:209], v[210:211], off offset:3072
	global_load_dwordx4 v[130:133], v[130:131], off
	v_or_b32_e32 v174, 16, v156
	v_ashrrev_i32_e32 v175, 31, v174
	v_or_b32_e32 v170, 32, v156
	v_ashrrev_i32_e32 v171, 31, v170
	v_or_b32_e32 v166, 48, v156
	v_ashrrev_i32_e32 v167, 31, v166
	v_add_u32_e32 v162, 0x80, v156
	v_ashrrev_i32_e32 v163, 31, v162
	v_add_u32_e32 v158, 0x90, v156
	v_ashrrev_i32_e32 v159, 31, v158
	v_add_u32_e32 v152, 0xa0, v156
	v_ashrrev_i32_e32 v153, 31, v152
	s_and_b64 vcc, exec, s[4:5]
	s_waitcnt vmcnt(0)
	v_mov_b32_e32 v148, v131
	v_mov_b32_e32 v149, v132
	v_mov_b32_e32 v131, v133
	v_pk_add_f32 v[130:131], v[148:149], v[130:131]
	s_nop 0
	v_add_f32_e32 v130, v130, v131
	v_mov_b32_e32 v131, v130
	s_nop 1
	v_permlane16_swap_b32 v131, v130
	s_waitcnt lgkmcnt(0)
	v_add_f32_e32 v130, v130, v131
	v_mov_b32_e32 v131, v130
	s_nop 1
	v_permlane32_swap_b32 v131, v130
	s_waitcnt lgkmcnt(0)
	v_add_f32_e32 v130, v130, v131
	v_fmamk_f32 v130, v130, 0x3a800000, v231
	v_rsq_f32_e32 v176, v130
	s_nop 1
	v_pk_mul_f32 v[122:123], v[122:123], v[176:177] op_sel_hi:[1,0]
	v_pk_mul_f32 v[124:125], v[124:125], v[176:177] op_sel_hi:[1,0]
	v_pk_mul_f32 v[126:127], v[126:127], v[176:177] op_sel_hi:[1,0]
	v_pk_mul_f32 v[128:129], v[128:129], v[176:177] op_sel_hi:[1,0]
	v_pk_mul_f32 v[118:119], v[118:119], v[176:177] op_sel_hi:[1,0]
	v_pk_mul_f32 v[120:121], v[120:121], v[176:177] op_sel_hi:[1,0]
	v_pk_mul_f32 v[114:115], v[114:115], v[176:177] op_sel_hi:[1,0]
	v_pk_mul_f32 v[116:117], v[116:117], v[176:177] op_sel_hi:[1,0]
	v_add_f32_e32 v130, v183, v182
	v_add_f32_e32 v131, v184, v185
	s_nop 0
	v_add_f32_e32 v130, v130, v131
	v_mov_b32_e32 v131, v130
	s_nop 1
	v_permlane16_swap_b32 v131, v130
	s_waitcnt lgkmcnt(0)
	v_add_f32_e32 v130, v130, v131
	v_mov_b32_e32 v131, v130
	s_nop 1
	v_permlane32_swap_b32 v131, v130
	s_waitcnt lgkmcnt(0)
	v_add_f32_e32 v130, v130, v131
	v_fmamk_f32 v130, v130, 0x3a800000, v231
	v_rsq_f32_e32 v172, v130
	s_nop 1
	v_pk_mul_f32 v[110:111], v[110:111], v[172:173] op_sel_hi:[1,0]
	v_pk_mul_f32 v[112:113], v[112:113], v[172:173] op_sel_hi:[1,0]
	v_pk_mul_f32 v[106:107], v[106:107], v[172:173] op_sel_hi:[1,0]
	v_pk_mul_f32 v[108:109], v[108:109], v[172:173] op_sel_hi:[1,0]
	v_pk_mul_f32 v[102:103], v[102:103], v[172:173] op_sel_hi:[1,0]
	v_pk_mul_f32 v[104:105], v[104:105], v[172:173] op_sel_hi:[1,0]
	v_pk_mul_f32 v[98:99], v[98:99], v[172:173] op_sel_hi:[1,0]
	v_pk_mul_f32 v[100:101], v[100:101], v[172:173] op_sel_hi:[1,0]
	v_add_f32_e32 v130, v187, v186
	v_add_f32_e32 v131, v188, v189
	s_nop 0
	v_add_f32_e32 v130, v130, v131
	v_mov_b32_e32 v131, v130
	s_nop 1
	v_permlane16_swap_b32 v131, v130
	s_waitcnt lgkmcnt(0)
	v_add_f32_e32 v130, v130, v131
	v_mov_b32_e32 v131, v130
	s_nop 1
	v_permlane32_swap_b32 v131, v130
	s_waitcnt lgkmcnt(0)
	v_add_f32_e32 v130, v130, v131
	v_fmamk_f32 v130, v130, 0x3a800000, v231
	v_rsq_f32_e32 v168, v130
	s_nop 1
	v_pk_mul_f32 v[94:95], v[94:95], v[168:169] op_sel_hi:[1,0]
	v_pk_mul_f32 v[96:97], v[96:97], v[168:169] op_sel_hi:[1,0]
	v_pk_mul_f32 v[90:91], v[90:91], v[168:169] op_sel_hi:[1,0]
	v_pk_mul_f32 v[92:93], v[92:93], v[168:169] op_sel_hi:[1,0]
	v_pk_mul_f32 v[86:87], v[86:87], v[168:169] op_sel_hi:[1,0]
	v_pk_mul_f32 v[88:89], v[88:89], v[168:169] op_sel_hi:[1,0]
	v_pk_mul_f32 v[82:83], v[82:83], v[168:169] op_sel_hi:[1,0]
	v_pk_mul_f32 v[84:85], v[84:85], v[168:169] op_sel_hi:[1,0]
	v_add_f32_e32 v130, v191, v190
	v_add_f32_e32 v131, v192, v193
	s_nop 0
	v_add_f32_e32 v130, v130, v131
	v_mov_b32_e32 v131, v130
	s_nop 1
	v_permlane16_swap_b32 v131, v130
	s_waitcnt lgkmcnt(0)
	v_add_f32_e32 v130, v130, v131
	v_mov_b32_e32 v131, v130
	s_nop 1
	v_permlane32_swap_b32 v131, v130
	s_waitcnt lgkmcnt(0)
	v_add_f32_e32 v130, v130, v131
	v_fmamk_f32 v130, v130, 0x3a800000, v231
	v_rsq_f32_e32 v164, v130
	s_nop 1
	v_pk_mul_f32 v[78:79], v[78:79], v[164:165] op_sel_hi:[1,0]
	v_pk_mul_f32 v[80:81], v[80:81], v[164:165] op_sel_hi:[1,0]
	v_pk_mul_f32 v[74:75], v[74:75], v[164:165] op_sel_hi:[1,0]
	v_pk_mul_f32 v[76:77], v[76:77], v[164:165] op_sel_hi:[1,0]
	v_pk_mul_f32 v[70:71], v[70:71], v[164:165] op_sel_hi:[1,0]
	v_pk_mul_f32 v[72:73], v[72:73], v[164:165] op_sel_hi:[1,0]
	v_pk_mul_f32 v[66:67], v[66:67], v[164:165] op_sel_hi:[1,0]
	v_pk_mul_f32 v[68:69], v[68:69], v[164:165] op_sel_hi:[1,0]
	v_add_f32_e32 v130, v195, v194
	v_add_f32_e32 v131, v196, v197
	s_nop 0
	v_add_f32_e32 v130, v130, v131
	v_mov_b32_e32 v131, v130
	s_nop 1
	v_permlane16_swap_b32 v131, v130
	s_waitcnt lgkmcnt(0)
	v_add_f32_e32 v130, v130, v131
	v_mov_b32_e32 v131, v130
	s_nop 1
	v_permlane32_swap_b32 v131, v130
	s_waitcnt lgkmcnt(0)
; __device__ __forceinline__ unsigned cvt_pk_bf16(float lo, float hi) { unsigned r; asm volatile("v_cvt_pk_bf16_f32 %0, %1, %2" : "=v"(r) : "v"(lo), "v"(hi)); return r; }
; __device__ __forceinline__ float row_rstd16_coop(const float* ssq, int row, int fq, float inv_n) {
;     const f32x4 a = *(const f32x4*)(ssq + (size_t)row * 16 + fq * 4);
;     float s = (a[0] + a[1]) + (a[2] + a[3]);
;     s += __shfl_xor(s, 16); s += __shfl_xor(s, 32);
;     return __builtin_amdgcn_rsqf(s * inv_n + EPS);
; }
;     __device__ __forceinline__ static float sg(float g, float uu) { return g * __builtin_amdgcn_rcpf(1.0f + __builtin_amdgcn_exp2f(-1.4426950408889634f * g)) * uu; }
;     __device__ __forceinline__ void operator()(const f32x4 (&acc)[2][2][4][2], const Unit& u, int wr, int wc, int fr, int fq) const {
;         const int row0 = u.pm * BM + wr * 64 + fr, col0 = u.pn * BM + wc * 32 + 8 * fq;
;         float rsv[2][4];
; #pragma unroll
;         for (int ai = 0; ai < 2; ++ai) {
; #pragma unroll
;             for (int m = 0; m < 4; ++m) rsv[ai][m] = row_rstd16_coop(ssq, row0 + ai * HALF + m * 16, fq, 1.0f / 1024.0f);
;         }
; #pragma unroll
;         for (int ai = 0; ai < 2; ++ai)
; #pragma unroll
;             for (int m = 0; m < 4; ++m) {
;                 const int row = row0 + ai * HALF + m * 16;
;                 const float rs = rsv[ai][m];
;                 bf16_t* rowp = H + (size_t)row * ldh + (col0 >> 1);
; #pragma unroll
;                 for (int bj = 0; bj < 2; ++bj) {
;                     const f32x4 v0 = acc[ai][bj][m][0] * rs, v1 = acc[ai][bj][m][1] * rs;
;                     u32x2 w; w.x = cvt_pk_bf16(sg(v0[0], v0[1]), sg(v0[2], v0[3])); w.y = cvt_pk_bf16(sg(v1[0], v1[1]), sg(v1[2], v1[3]));
;                     *(u32x2*)(rowp + bj * (HALF / 2)) = w;
;                 }
	v_add_f32_e32 v130, v130, v131
	v_fmamk_f32 v130, v130, 0x3a800000, v231
	v_rsq_f32_e32 v160, v130
	s_nop 1
	v_pk_mul_f32 v[62:63], v[62:63], v[160:161] op_sel_hi:[1,0]
	v_pk_mul_f32 v[64:65], v[64:65], v[160:161] op_sel_hi:[1,0]
	v_pk_mul_f32 v[58:59], v[58:59], v[160:161] op_sel_hi:[1,0]
	v_pk_mul_f32 v[60:61], v[60:61], v[160:161] op_sel_hi:[1,0]
	v_pk_mul_f32 v[54:55], v[54:55], v[160:161] op_sel_hi:[1,0]
	v_pk_mul_f32 v[56:57], v[56:57], v[160:161] op_sel_hi:[1,0]
	v_pk_mul_f32 v[50:51], v[50:51], v[160:161] op_sel_hi:[1,0]
	v_pk_mul_f32 v[52:53], v[52:53], v[160:161] op_sel_hi:[1,0]
	v_add_f32_e32 v130, v199, v198
	v_add_f32_e32 v131, v200, v201
	s_nop 0
	v_add_f32_e32 v130, v130, v131
	v_mov_b32_e32 v131, v130
	s_nop 1
	v_permlane16_swap_b32 v131, v130
	s_waitcnt lgkmcnt(0)
	v_add_f32_e32 v130, v130, v131
	v_mov_b32_e32 v131, v130
	s_nop 1
	v_permlane32_swap_b32 v131, v130
	s_waitcnt lgkmcnt(0)
	v_add_f32_e32 v130, v130, v131
	v_fmamk_f32 v130, v130, 0x3a800000, v231
	v_rsq_f32_e32 v154, v130
	s_nop 1
	v_pk_mul_f32 v[46:47], v[46:47], v[154:155] op_sel_hi:[1,0]
	v_pk_mul_f32 v[48:49], v[48:49], v[154:155] op_sel_hi:[1,0]
	v_pk_mul_f32 v[42:43], v[42:43], v[154:155] op_sel_hi:[1,0]
	v_pk_mul_f32 v[44:45], v[44:45], v[154:155] op_sel_hi:[1,0]
	v_pk_mul_f32 v[38:39], v[38:39], v[154:155] op_sel_hi:[1,0]
	v_pk_mul_f32 v[40:41], v[40:41], v[154:155] op_sel_hi:[1,0]
	v_pk_mul_f32 v[34:35], v[34:35], v[154:155] op_sel_hi:[1,0]
	v_pk_mul_f32 v[36:37], v[36:37], v[154:155] op_sel_hi:[1,0]
	v_add_f32_e32 v130, v203, v202
	v_add_f32_e32 v131, v204, v205
	v_add_u32_e32 v148, 0xb0, v156
	v_add_f32_e32 v130, v130, v131
	v_mov_b32_e32 v131, v130
	s_nop 1
	v_permlane16_swap_b32 v131, v130
	v_ashrrev_i32_e32 v149, 31, v148
	s_waitcnt lgkmcnt(0)
	v_add_f32_e32 v130, v130, v131
	v_mov_b32_e32 v131, v130
	s_nop 1
	v_permlane32_swap_b32 v131, v130
	s_waitcnt lgkmcnt(0)
	v_add_f32_e32 v130, v130, v131
	v_fmamk_f32 v130, v130, 0x3a800000, v231
	v_rsq_f32_e32 v150, v130
	s_nop 1
	v_pk_mul_f32 v[30:31], v[30:31], v[150:151] op_sel_hi:[1,0]
	v_pk_mul_f32 v[32:33], v[32:33], v[150:151] op_sel_hi:[1,0]
	v_pk_mul_f32 v[26:27], v[26:27], v[150:151] op_sel_hi:[1,0]
	v_pk_mul_f32 v[28:29], v[28:29], v[150:151] op_sel_hi:[1,0]
	v_pk_mul_f32 v[22:23], v[22:23], v[150:151] op_sel_hi:[1,0]
	v_pk_mul_f32 v[24:25], v[24:25], v[150:151] op_sel_hi:[1,0]
	v_pk_mul_f32 v[18:19], v[18:19], v[150:151] op_sel_hi:[1,0]
	v_pk_mul_f32 v[20:21], v[20:21], v[150:151] op_sel_hi:[1,0]
	v_add_f32_e32 v130, v207, v206
	v_add_f32_e32 v131, v208, v209
	v_mov_b64_e32 v[132:133], s[16:17]
	v_add_f32_e32 v130, v130, v131
	v_mov_b32_e32 v131, v130
	s_nop 1
	v_permlane16_swap_b32 v131, v130
	v_mad_i64_i32 v[180:181], s[24:25], v156, s96, v[132:133]
	s_waitcnt lgkmcnt(0)
	v_add_f32_e32 v130, v130, v131
	v_mov_b32_e32 v131, v130
	s_nop 1
	v_permlane32_swap_b32 v131, v130
	s_waitcnt lgkmcnt(0)
	v_add_f32_e32 v130, v130, v131
	v_lshl_or_b32 v131, s51, 8, v155
	v_ashrrev_i32_e32 v178, 1, v131
	v_mul_f32_e32 v131, 0xbfb8aa3b, v122
	v_exp_f32_e32 v131, v131
	v_ashrrev_i32_e32 v179, 31, v178
	v_lshlrev_b64 v[156:157], 1, v[178:179]
	v_lshl_add_u64 v[178:179], v[180:181], 0, v[156:157]
	v_add_f32_e32 v131, 1.0, v131
	v_rcp_f32_e32 v131, v131
	v_fmamk_f32 v130, v130, 0x3a800000, v231
	v_rsq_f32_e32 v130, v130
	v_mul_f32_e32 v122, v122, v131
	v_mul_f32_e32 v122, v123, v122
	v_mul_f32_e32 v123, 0xbfb8aa3b, v124
	v_exp_f32_e32 v123, v123
	v_pk_mul_f32 v[14:15], v[14:15], v[130:131] op_sel_hi:[1,0]
	v_pk_mul_f32 v[16:17], v[16:17], v[130:131] op_sel_hi:[1,0]
	v_pk_mul_f32 v[10:11], v[10:11], v[130:131] op_sel_hi:[1,0]
	v_add_f32_e32 v123, 1.0, v123
	v_rcp_f32_e32 v123, v123
	v_pk_mul_f32 v[12:13], v[12:13], v[130:131] op_sel_hi:[1,0]
	v_pk_mul_f32 v[6:7], v[6:7], v[130:131] op_sel_hi:[1,0]
	v_pk_mul_f32 v[8:9], v[8:9], v[130:131] op_sel_hi:[1,0]
	v_mul_f32_e32 v123, v124, v123
	v_mul_f32_e32 v123, v125, v123
	v_cvt_pk_bf16_f32 v122, v122, v123
	v_mul_f32_e32 v123, 0xbfb8aa3b, v126
	v_exp_f32_e32 v123, v123
	v_mul_f32_e32 v124, 0xbfb8aa3b, v128
	v_exp_f32_e32 v124, v124
	v_pk_mul_f32 v[2:3], v[2:3], v[130:131] op_sel_hi:[1,0]
	v_add_f32_e32 v123, 1.0, v123
	v_rcp_f32_e32 v123, v123
	v_add_f32_e32 v124, 1.0, v124
	v_rcp_f32_e32 v124, v124
	v_pk_mul_f32 v[4:5], v[4:5], v[130:131] op_sel_hi:[1,0]
	v_mul_f32_e32 v123, v126, v123
	v_mul_f32_e32 v123, v127, v123
	v_mul_f32_e32 v124, v128, v124
	v_mul_f32_e32 v124, v129, v124
	v_cvt_pk_bf16_f32 v123, v123, v124
	global_store_dwordx2 v[178:179], v[122:123], off
	v_mul_f32_e32 v122, 0xbfb8aa3b, v118
	v_exp_f32_e32 v122, v122
	s_nop 0
	v_add_f32_e32 v122, 1.0, v122
	v_rcp_f32_e32 v122, v122
	s_nop 0
	v_mul_f32_e32 v118, v118, v122
	v_mul_f32_e32 v118, v119, v118
	v_mul_f32_e32 v119, 0xbfb8aa3b, v120
	v_exp_f32_e32 v119, v119
	s_nop 0
	v_add_f32_e32 v119, 1.0, v119
	v_rcp_f32_e32 v119, v119
	s_nop 0
	v_mul_f32_e32 v119, v120, v119
	v_mul_f32_e32 v119, v121, v119
	v_cvt_pk_bf16_f32 v118, v118, v119
	v_mul_f32_e32 v119, 0xbfb8aa3b, v114
	v_exp_f32_e32 v119, v119
	s_nop 0
	v_add_f32_e32 v119, 1.0, v119
	v_rcp_f32_e32 v119, v119
	s_nop 0
	v_mul_f32_e32 v114, v114, v119
	v_mul_f32_e32 v114, v115, v114
	v_mul_f32_e32 v115, 0xbfb8aa3b, v116
	v_exp_f32_e32 v115, v115
	s_nop 0
	v_add_f32_e32 v115, 1.0, v115
	v_rcp_f32_e32 v115, v115
	s_nop 0
	v_mul_f32_e32 v115, v116, v115
	v_mul_f32_e32 v116, 0xbfb8aa3b, v110
	v_exp_f32_e32 v116, v116
	v_mul_f32_e32 v115, v117, v115
	v_cvt_pk_bf16_f32 v119, v114, v115
	global_store_dwordx2 v[178:179], v[118:119], off offset:128
	v_add_f32_e32 v116, 1.0, v116
	v_rcp_f32_e32 v116, v116
	v_mad_i64_i32 v[114:115], s[24:25], v174, s96, v[132:133]
; __device__ __forceinline__ unsigned cvt_pk_bf16(float lo, float hi) { unsigned r; asm volatile("v_cvt_pk_bf16_f32 %0, %1, %2" : "=v"(r) : "v"(lo), "v"(hi)); return r; }
;     __device__ __forceinline__ static float sg(float g, float uu) { return g * __builtin_amdgcn_rcpf(1.0f + __builtin_amdgcn_exp2f(-1.4426950408889634f * g)) * uu; }
;     __device__ __forceinline__ void operator()(const f32x4 (&acc)[2][2][4][2], const Unit& u, int wr, int wc, int fr, int fq) const {
;         const int row0 = u.pm * BM + wr * 64 + fr, col0 = u.pn * BM + wc * 32 + 8 * fq;
;         float rsv[2][4];
; #pragma unroll
;         for (int ai = 0; ai < 2; ++ai) {
; #pragma unroll
;             for (int m = 0; m < 4; ++m) rsv[ai][m] = row_rstd16_coop(ssq, row0 + ai * HALF + m * 16, fq, 1.0f / 1024.0f);
;         }
; #pragma unroll
;         for (int ai = 0; ai < 2; ++ai)
; #pragma unroll
;             for (int m = 0; m < 4; ++m) {
;                 const int row = row0 + ai * HALF + m * 16;
;                 const float rs = rsv[ai][m];
;                 bf16_t* rowp = H + (size_t)row * ldh + (col0 >> 1);
; #pragma unroll
;                 for (int bj = 0; bj < 2; ++bj) {
;                     const f32x4 v0 = acc[ai][bj][m][0] * rs, v1 = acc[ai][bj][m][1] * rs;
;                     u32x2 w; w.x = cvt_pk_bf16(sg(v0[0], v0[1]), sg(v0[2], v0[3])); w.y = cvt_pk_bf16(sg(v1[0], v1[1]), sg(v1[2], v1[3]));
;                     *(u32x2*)(rowp + bj * (HALF / 2)) = w;
;                 }
	v_lshl_add_u64 v[114:115], v[114:115], 0, v[156:157]
	v_mul_f32_e32 v110, v110, v116
	v_mul_f32_e32 v110, v111, v110
	v_mul_f32_e32 v111, 0xbfb8aa3b, v112
	v_exp_f32_e32 v111, v111
	s_nop 0
	v_add_f32_e32 v111, 1.0, v111
	v_rcp_f32_e32 v111, v111
	s_nop 0
	v_mul_f32_e32 v111, v112, v111
	v_mul_f32_e32 v111, v113, v111
	v_cvt_pk_bf16_f32 v110, v110, v111
	v_mul_f32_e32 v111, 0xbfb8aa3b, v106
	v_exp_f32_e32 v111, v111
	s_nop 0
	v_add_f32_e32 v111, 1.0, v111
	v_rcp_f32_e32 v111, v111
	s_nop 0
	v_mul_f32_e32 v106, v106, v111
	v_mul_f32_e32 v106, v107, v106
	v_mul_f32_e32 v107, 0xbfb8aa3b, v108
	v_exp_f32_e32 v107, v107
	s_nop 0
	v_add_f32_e32 v107, 1.0, v107
	v_rcp_f32_e32 v107, v107
	s_nop 0
	v_mul_f32_e32 v107, v108, v107
	v_mul_f32_e32 v107, v109, v107
	v_cvt_pk_bf16_f32 v111, v106, v107
	v_mul_f32_e32 v106, 0xbfb8aa3b, v102
	v_exp_f32_e32 v106, v106
	global_store_dwordx2 v[114:115], v[110:111], off
	v_add_f32_e32 v106, 1.0, v106
	v_rcp_f32_e32 v106, v106
	s_nop 0
	v_mul_f32_e32 v102, v102, v106
	v_mul_f32_e32 v102, v103, v102
	v_mul_f32_e32 v103, 0xbfb8aa3b, v104
	v_exp_f32_e32 v103, v103
	s_nop 0
	v_add_f32_e32 v103, 1.0, v103
	v_rcp_f32_e32 v103, v103
	s_nop 0
	v_mul_f32_e32 v103, v104, v103
	v_mul_f32_e32 v103, v105, v103
	v_cvt_pk_bf16_f32 v102, v102, v103
	v_mul_f32_e32 v103, 0xbfb8aa3b, v98
	v_exp_f32_e32 v103, v103
	s_nop 0
	v_add_f32_e32 v103, 1.0, v103
	v_rcp_f32_e32 v103, v103
	s_nop 0
	v_mul_f32_e32 v98, v98, v103
	v_mul_f32_e32 v98, v99, v98
	v_mul_f32_e32 v99, 0xbfb8aa3b, v100
	v_exp_f32_e32 v99, v99
	s_nop 0
	v_add_f32_e32 v99, 1.0, v99
	v_rcp_f32_e32 v99, v99
	s_nop 0
	v_mul_f32_e32 v99, v100, v99
	v_mul_f32_e32 v100, 0xbfb8aa3b, v94
	v_exp_f32_e32 v100, v100
	v_mul_f32_e32 v99, v101, v99
	v_cvt_pk_bf16_f32 v103, v98, v99
	global_store_dwordx2 v[114:115], v[102:103], off offset:128
	v_add_f32_e32 v100, 1.0, v100
	v_rcp_f32_e32 v100, v100
	v_mad_i64_i32 v[98:99], s[24:25], v170, s96, v[132:133]
	v_lshl_add_u64 v[98:99], v[98:99], 0, v[156:157]
	v_mul_f32_e32 v94, v94, v100
	v_mul_f32_e32 v94, v95, v94
	v_mul_f32_e32 v95, 0xbfb8aa3b, v96
	v_exp_f32_e32 v95, v95
	s_nop 0
	v_add_f32_e32 v95, 1.0, v95
	v_rcp_f32_e32 v95, v95
	s_nop 0
	v_mul_f32_e32 v95, v96, v95
	v_mul_f32_e32 v95, v97, v95
	v_cvt_pk_bf16_f32 v94, v94, v95
	v_mul_f32_e32 v95, 0xbfb8aa3b, v90
	v_exp_f32_e32 v95, v95
	s_nop 0
	v_add_f32_e32 v95, 1.0, v95
	v_rcp_f32_e32 v95, v95
	s_nop 0
	v_mul_f32_e32 v90, v90, v95
	v_mul_f32_e32 v90, v91, v90
	v_mul_f32_e32 v91, 0xbfb8aa3b, v92
	v_exp_f32_e32 v91, v91
	s_nop 0
	v_add_f32_e32 v91, 1.0, v91
	v_rcp_f32_e32 v91, v91
	s_nop 0
	v_mul_f32_e32 v91, v92, v91
	v_mul_f32_e32 v91, v93, v91
	v_cvt_pk_bf16_f32 v95, v90, v91
	v_mul_f32_e32 v90, 0xbfb8aa3b, v86
	v_exp_f32_e32 v90, v90
	global_store_dwordx2 v[98:99], v[94:95], off
	v_add_f32_e32 v90, 1.0, v90
	v_rcp_f32_e32 v90, v90
	s_nop 0
	v_mul_f32_e32 v86, v86, v90
	v_mul_f32_e32 v86, v87, v86
	v_mul_f32_e32 v87, 0xbfb8aa3b, v88
	v_exp_f32_e32 v87, v87
	s_nop 0
	v_add_f32_e32 v87, 1.0, v87
	v_rcp_f32_e32 v87, v87
	s_nop 0
	v_mul_f32_e32 v87, v88, v87
	v_mul_f32_e32 v87, v89, v87
	v_cvt_pk_bf16_f32 v86, v86, v87
	v_mul_f32_e32 v87, 0xbfb8aa3b, v82
	v_exp_f32_e32 v87, v87
	s_nop 0
	v_add_f32_e32 v87, 1.0, v87
	v_rcp_f32_e32 v87, v87
	s_nop 0
	v_mul_f32_e32 v82, v82, v87
	v_mul_f32_e32 v82, v83, v82
	v_mul_f32_e32 v83, 0xbfb8aa3b, v84
	v_exp_f32_e32 v83, v83
	s_nop 0
	v_add_f32_e32 v83, 1.0, v83
	v_rcp_f32_e32 v83, v83
	s_nop 0
	v_mul_f32_e32 v83, v84, v83
	v_mul_f32_e32 v84, 0xbfb8aa3b, v78
	v_exp_f32_e32 v84, v84
	v_mul_f32_e32 v83, v85, v83
	v_cvt_pk_bf16_f32 v87, v82, v83
	global_store_dwordx2 v[98:99], v[86:87], off offset:128
	v_add_f32_e32 v84, 1.0, v84
	v_rcp_f32_e32 v84, v84
	v_mad_i64_i32 v[82:83], s[24:25], v166, s96, v[132:133]
	v_lshl_add_u64 v[82:83], v[82:83], 0, v[156:157]
	v_mul_f32_e32 v78, v78, v84
	v_mul_f32_e32 v78, v79, v78
	v_mul_f32_e32 v79, 0xbfb8aa3b, v80
	v_exp_f32_e32 v79, v79
	s_nop 0
	v_add_f32_e32 v79, 1.0, v79
	v_rcp_f32_e32 v79, v79
	s_nop 0
	v_mul_f32_e32 v79, v80, v79
	v_mul_f32_e32 v79, v81, v79
	v_cvt_pk_bf16_f32 v78, v78, v79
	v_mul_f32_e32 v79, 0xbfb8aa3b, v74
	v_exp_f32_e32 v79, v79
	s_nop 0
	v_add_f32_e32 v79, 1.0, v79
	v_rcp_f32_e32 v79, v79
	s_nop 0
	v_mul_f32_e32 v74, v74, v79
	v_mul_f32_e32 v74, v75, v74
	v_mul_f32_e32 v75, 0xbfb8aa3b, v76
	v_exp_f32_e32 v75, v75
	s_nop 0
	v_add_f32_e32 v75, 1.0, v75
	v_rcp_f32_e32 v75, v75
	s_nop 0
	v_mul_f32_e32 v75, v76, v75
	v_mul_f32_e32 v75, v77, v75
	v_cvt_pk_bf16_f32 v79, v74, v75
	v_mul_f32_e32 v74, 0xbfb8aa3b, v70
	v_exp_f32_e32 v74, v74
	global_store_dwordx2 v[82:83], v[78:79], off
	v_add_f32_e32 v74, 1.0, v74
	v_rcp_f32_e32 v74, v74
	s_nop 0
	v_mul_f32_e32 v70, v70, v74
	v_mul_f32_e32 v70, v71, v70
	v_mul_f32_e32 v71, 0xbfb8aa3b, v72
	v_exp_f32_e32 v71, v71
	s_nop 0
	v_add_f32_e32 v71, 1.0, v71
	v_rcp_f32_e32 v71, v71
	s_nop 0
	v_mul_f32_e32 v71, v72, v71
	v_mul_f32_e32 v71, v73, v71
	v_cvt_pk_bf16_f32 v70, v70, v71
	v_mul_f32_e32 v71, 0xbfb8aa3b, v66
	v_exp_f32_e32 v71, v71
	s_nop 0
	v_add_f32_e32 v71, 1.0, v71
	v_rcp_f32_e32 v71, v71
	s_nop 0
	v_mul_f32_e32 v66, v66, v71
	v_mul_f32_e32 v66, v67, v66
	v_mul_f32_e32 v67, 0xbfb8aa3b, v68
	v_exp_f32_e32 v67, v67
	s_nop 0
	v_add_f32_e32 v67, 1.0, v67
	v_rcp_f32_e32 v67, v67
	s_nop 0
	v_mul_f32_e32 v67, v68, v67
	v_mul_f32_e32 v68, 0xbfb8aa3b, v62
	v_exp_f32_e32 v68, v68
	v_mul_f32_e32 v67, v69, v67
	v_cvt_pk_bf16_f32 v71, v66, v67
	global_store_dwordx2 v[82:83], v[70:71], off offset:128
	v_add_f32_e32 v68, 1.0, v68
	v_rcp_f32_e32 v68, v68
	v_mad_i64_i32 v[66:67], s[24:25], v162, s96, v[132:133]
	v_lshl_add_u64 v[66:67], v[66:67], 0, v[156:157]
; __device__ __forceinline__ unsigned cvt_pk_bf16(float lo, float hi) { unsigned r; asm volatile("v_cvt_pk_bf16_f32 %0, %1, %2" : "=v"(r) : "v"(lo), "v"(hi)); return r; }
;     __device__ __forceinline__ static float sg(float g, float uu) { return g * __builtin_amdgcn_rcpf(1.0f + __builtin_amdgcn_exp2f(-1.4426950408889634f * g)) * uu; }
;     __device__ __forceinline__ void operator()(const f32x4 (&acc)[2][2][4][2], const Unit& u, int wr, int wc, int fr, int fq) const {
;         const int row0 = u.pm * BM + wr * 64 + fr, col0 = u.pn * BM + wc * 32 + 8 * fq;
;         float rsv[2][4];
; #pragma unroll
;         for (int ai = 0; ai < 2; ++ai) {
; #pragma unroll
;             for (int m = 0; m < 4; ++m) rsv[ai][m] = row_rstd16_coop(ssq, row0 + ai * HALF + m * 16, fq, 1.0f / 1024.0f);
;         }
; #pragma unroll
;         for (int ai = 0; ai < 2; ++ai)
; #pragma unroll
;             for (int m = 0; m < 4; ++m) {
;                 const int row = row0 + ai * HALF + m * 16;
;                 const float rs = rsv[ai][m];
;                 bf16_t* rowp = H + (size_t)row * ldh + (col0 >> 1);
; #pragma unroll
;                 for (int bj = 0; bj < 2; ++bj) {
;                     const f32x4 v0 = acc[ai][bj][m][0] * rs, v1 = acc[ai][bj][m][1] * rs;
;                     u32x2 w; w.x = cvt_pk_bf16(sg(v0[0], v0[1]), sg(v0[2], v0[3])); w.y = cvt_pk_bf16(sg(v1[0], v1[1]), sg(v1[2], v1[3]));
;                     *(u32x2*)(rowp + bj * (HALF / 2)) = w;
;                 }
	v_mul_f32_e32 v62, v62, v68
	v_mul_f32_e32 v62, v63, v62
	v_mul_f32_e32 v63, 0xbfb8aa3b, v64
	v_exp_f32_e32 v63, v63
	s_nop 0
	v_add_f32_e32 v63, 1.0, v63
	v_rcp_f32_e32 v63, v63
	s_nop 0
	v_mul_f32_e32 v63, v64, v63
	v_mul_f32_e32 v63, v65, v63
	v_cvt_pk_bf16_f32 v62, v62, v63
	v_mul_f32_e32 v63, 0xbfb8aa3b, v58
	v_exp_f32_e32 v63, v63
	s_nop 0
	v_add_f32_e32 v63, 1.0, v63
	v_rcp_f32_e32 v63, v63
	s_nop 0
	v_mul_f32_e32 v58, v58, v63
	v_mul_f32_e32 v58, v59, v58
	v_mul_f32_e32 v59, 0xbfb8aa3b, v60
	v_exp_f32_e32 v59, v59
	s_nop 0
	v_add_f32_e32 v59, 1.0, v59
	v_rcp_f32_e32 v59, v59
	s_nop 0
	v_mul_f32_e32 v59, v60, v59
	v_mul_f32_e32 v59, v61, v59
	v_cvt_pk_bf16_f32 v63, v58, v59
	v_mul_f32_e32 v58, 0xbfb8aa3b, v54
	v_exp_f32_e32 v58, v58
	global_store_dwordx2 v[66:67], v[62:63], off
	v_add_f32_e32 v58, 1.0, v58
	v_rcp_f32_e32 v58, v58
	s_nop 0
	v_mul_f32_e32 v54, v54, v58
	v_mul_f32_e32 v54, v55, v54
	v_mul_f32_e32 v55, 0xbfb8aa3b, v56
	v_exp_f32_e32 v55, v55
	s_nop 0
	v_add_f32_e32 v55, 1.0, v55
	v_rcp_f32_e32 v55, v55
	s_nop 0
	v_mul_f32_e32 v55, v56, v55
	v_mul_f32_e32 v55, v57, v55
	v_cvt_pk_bf16_f32 v54, v54, v55
	v_mul_f32_e32 v55, 0xbfb8aa3b, v50
	v_exp_f32_e32 v55, v55
	s_nop 0
	v_add_f32_e32 v55, 1.0, v55
	v_rcp_f32_e32 v55, v55
	s_nop 0
	v_mul_f32_e32 v50, v50, v55
	v_mul_f32_e32 v50, v51, v50
	v_mul_f32_e32 v51, 0xbfb8aa3b, v52
	v_exp_f32_e32 v51, v51
	s_nop 0
	v_add_f32_e32 v51, 1.0, v51
	v_rcp_f32_e32 v51, v51
	s_nop 0
	v_mul_f32_e32 v51, v52, v51
	v_mul_f32_e32 v52, 0xbfb8aa3b, v46
	v_exp_f32_e32 v52, v52
	v_mul_f32_e32 v51, v53, v51
	v_cvt_pk_bf16_f32 v55, v50, v51
	global_store_dwordx2 v[66:67], v[54:55], off offset:128
	v_add_f32_e32 v52, 1.0, v52
	v_rcp_f32_e32 v52, v52
	v_mad_i64_i32 v[50:51], s[24:25], v158, s96, v[132:133]
	v_lshl_add_u64 v[50:51], v[50:51], 0, v[156:157]
	v_mul_f32_e32 v46, v46, v52
	v_mul_f32_e32 v46, v47, v46
	v_mul_f32_e32 v47, 0xbfb8aa3b, v48
	v_exp_f32_e32 v47, v47
	s_nop 0
	v_add_f32_e32 v47, 1.0, v47
	v_rcp_f32_e32 v47, v47
	s_nop 0
	v_mul_f32_e32 v47, v48, v47
	v_mul_f32_e32 v47, v49, v47
	v_cvt_pk_bf16_f32 v46, v46, v47
	v_mul_f32_e32 v47, 0xbfb8aa3b, v42
	v_exp_f32_e32 v47, v47
	s_nop 0
	v_add_f32_e32 v47, 1.0, v47
	v_rcp_f32_e32 v47, v47
	s_nop 0
	v_mul_f32_e32 v42, v42, v47
	v_mul_f32_e32 v42, v43, v42
	v_mul_f32_e32 v43, 0xbfb8aa3b, v44
	v_exp_f32_e32 v43, v43
	s_nop 0
	v_add_f32_e32 v43, 1.0, v43
	v_rcp_f32_e32 v43, v43
	s_nop 0
	v_mul_f32_e32 v43, v44, v43
	v_mul_f32_e32 v43, v45, v43
	v_cvt_pk_bf16_f32 v47, v42, v43
	v_mul_f32_e32 v42, 0xbfb8aa3b, v38
	v_exp_f32_e32 v42, v42
	global_store_dwordx2 v[50:51], v[46:47], off
	v_add_f32_e32 v42, 1.0, v42
	v_rcp_f32_e32 v42, v42
	s_nop 0
	v_mul_f32_e32 v38, v38, v42
	v_mul_f32_e32 v38, v39, v38
	v_mul_f32_e32 v39, 0xbfb8aa3b, v40
	v_exp_f32_e32 v39, v39
	s_nop 0
	v_add_f32_e32 v39, 1.0, v39
	v_rcp_f32_e32 v39, v39
	s_nop 0
	v_mul_f32_e32 v39, v40, v39
	v_mul_f32_e32 v39, v41, v39
	v_cvt_pk_bf16_f32 v38, v38, v39
	v_mul_f32_e32 v39, 0xbfb8aa3b, v34
	v_exp_f32_e32 v39, v39
	s_nop 0
	v_add_f32_e32 v39, 1.0, v39
	v_rcp_f32_e32 v39, v39
	s_nop 0
	v_mul_f32_e32 v34, v34, v39
	v_mul_f32_e32 v34, v35, v34
	v_mul_f32_e32 v35, 0xbfb8aa3b, v36
	v_exp_f32_e32 v35, v35
	s_nop 0
	v_add_f32_e32 v35, 1.0, v35
	v_rcp_f32_e32 v35, v35
	s_nop 0
	v_mul_f32_e32 v35, v36, v35
	v_mul_f32_e32 v36, 0xbfb8aa3b, v30
	v_exp_f32_e32 v36, v36
	v_mul_f32_e32 v35, v37, v35
	v_cvt_pk_bf16_f32 v39, v34, v35
	global_store_dwordx2 v[50:51], v[38:39], off offset:128
	v_add_f32_e32 v36, 1.0, v36
	v_rcp_f32_e32 v36, v36
	v_mad_i64_i32 v[34:35], s[24:25], v152, s96, v[132:133]
; __device__ __forceinline__ unsigned cvt_pk_bf16(float lo, float hi) { unsigned r; asm volatile("v_cvt_pk_bf16_f32 %0, %1, %2" : "=v"(r) : "v"(lo), "v"(hi)); return r; }
; #define PG8_BAR __builtin_amdgcn_s_barrier()
; template <class Epi, class Sched, bool ALIGN_EPI = false, bool SP2 = false>
; __device__ __forceinline__ void gemm_phase(PG8_LAS unsigned char* lds, const Gemm g, const Sched& S, const Epi& E) {
;     ...
;         if constexpr (ALIGN_EPI) { if (wr == 0) PG8_BAR; }
;         if constexpr (!Epi::AFTER_DRAIN) { E(acc, cur, wr, wc, fr, fq); S.done(cur); }
;         if (!has_next) break;
; #pragma unroll
;         for (int a = 0; a < 2; ++a)
; #pragma unroll
;             for (int b = 0; b < 2; ++b)
; #pragma unroll
;                 for (int m = 0; m < 4; ++m)
; #pragma unroll
;                     for (int n = 0; n < 2; ++n) acc[a][b][m][n] = (f32x4){0.f, 0.f, 0.f, 0.f};
;         cur = nxt; cA = nA; cB = nB; ++ui;
;         if constexpr (ALIGN_EPI) { if (wr == 1) PG8_BAR; }
;     __device__ __forceinline__ static float sg(float g, float uu) { return g * __builtin_amdgcn_rcpf(1.0f + __builtin_amdgcn_exp2f(-1.4426950408889634f * g)) * uu; }
;     __device__ __forceinline__ void operator()(const f32x4 (&acc)[2][2][4][2], const Unit& u, int wr, int wc, int fr, int fq) const {
;         const int row0 = u.pm * BM + wr * 64 + fr, col0 = u.pn * BM + wc * 32 + 8 * fq;
;         float rsv[2][4];
; #pragma unroll
;         for (int ai = 0; ai < 2; ++ai) {
; #pragma unroll
;             for (int m = 0; m < 4; ++m) rsv[ai][m] = row_rstd16_coop(ssq, row0 + ai * HALF + m * 16, fq, 1.0f / 1024.0f);
;         }
; #pragma unroll
;         for (int ai = 0; ai < 2; ++ai)
; #pragma unroll
;             for (int m = 0; m < 4; ++m) {
;                 const int row = row0 + ai * HALF + m * 16;
;                 const float rs = rsv[ai][m];
;                 bf16_t* rowp = H + (size_t)row * ldh + (col0 >> 1);
; #pragma unroll
;                 for (int bj = 0; bj < 2; ++bj) {
;                     const f32x4 v0 = acc[ai][bj][m][0] * rs, v1 = acc[ai][bj][m][1] * rs;
;                     u32x2 w; w.x = cvt_pk_bf16(sg(v0[0], v0[1]), sg(v0[2], v0[3])); w.y = cvt_pk_bf16(sg(v1[0], v1[1]), sg(v1[2], v1[3]));
;                     *(u32x2*)(rowp + bj * (HALF / 2)) = w;
;                 }
	v_lshl_add_u64 v[34:35], v[34:35], 0, v[156:157]
	v_mul_f32_e32 v30, v30, v36
	v_mul_f32_e32 v30, v31, v30
	v_mul_f32_e32 v31, 0xbfb8aa3b, v32
	v_exp_f32_e32 v31, v31
	s_nop 0
	v_add_f32_e32 v31, 1.0, v31
	v_rcp_f32_e32 v31, v31
	s_nop 0
	v_mul_f32_e32 v31, v32, v31
	v_mul_f32_e32 v31, v33, v31
	v_cvt_pk_bf16_f32 v30, v30, v31
	v_mul_f32_e32 v31, 0xbfb8aa3b, v26
	v_exp_f32_e32 v31, v31
	s_nop 0
	v_add_f32_e32 v31, 1.0, v31
	v_rcp_f32_e32 v31, v31
	s_nop 0
	v_mul_f32_e32 v26, v26, v31
	v_mul_f32_e32 v26, v27, v26
	v_mul_f32_e32 v27, 0xbfb8aa3b, v28
	v_exp_f32_e32 v27, v27
	s_nop 0
	v_add_f32_e32 v27, 1.0, v27
	v_rcp_f32_e32 v27, v27
	s_nop 0
	v_mul_f32_e32 v27, v28, v27
	v_mul_f32_e32 v27, v29, v27
	v_cvt_pk_bf16_f32 v31, v26, v27
	v_mul_f32_e32 v26, 0xbfb8aa3b, v22
	v_exp_f32_e32 v26, v26
	global_store_dwordx2 v[34:35], v[30:31], off
	v_add_f32_e32 v26, 1.0, v26
	v_rcp_f32_e32 v26, v26
	s_nop 0
	v_mul_f32_e32 v22, v22, v26
	v_mul_f32_e32 v22, v23, v22
	v_mul_f32_e32 v23, 0xbfb8aa3b, v24
	v_exp_f32_e32 v23, v23
	s_nop 0
	v_add_f32_e32 v23, 1.0, v23
	v_rcp_f32_e32 v23, v23
	s_nop 0
	v_mul_f32_e32 v23, v24, v23
	v_mul_f32_e32 v23, v25, v23
	v_cvt_pk_bf16_f32 v22, v22, v23
	v_mul_f32_e32 v23, 0xbfb8aa3b, v18
	v_exp_f32_e32 v23, v23
	s_nop 0
	v_add_f32_e32 v23, 1.0, v23
	v_rcp_f32_e32 v23, v23
	s_nop 0
	v_mul_f32_e32 v18, v18, v23
	v_mul_f32_e32 v18, v19, v18
	v_mul_f32_e32 v19, 0xbfb8aa3b, v20
	v_exp_f32_e32 v19, v19
	s_nop 0
	v_add_f32_e32 v19, 1.0, v19
	v_rcp_f32_e32 v19, v19
	s_nop 0
	v_mul_f32_e32 v19, v20, v19
	v_mul_f32_e32 v20, 0xbfb8aa3b, v14
	v_exp_f32_e32 v20, v20
	v_mul_f32_e32 v19, v21, v19
	v_cvt_pk_bf16_f32 v23, v18, v19
	global_store_dwordx2 v[34:35], v[22:23], off offset:128
	v_add_f32_e32 v20, 1.0, v20
	v_rcp_f32_e32 v20, v20
	v_mad_i64_i32 v[18:19], s[24:25], v148, s96, v[132:133]
	v_lshl_add_u64 v[18:19], v[18:19], 0, v[156:157]
	v_mul_f32_e32 v14, v14, v20
	v_mul_f32_e32 v14, v15, v14
	v_mul_f32_e32 v15, 0xbfb8aa3b, v16
	v_exp_f32_e32 v15, v15
	s_mov_b64 s[24:25], -1
	v_add_f32_e32 v15, 1.0, v15
	v_rcp_f32_e32 v15, v15
	s_nop 0
	v_mul_f32_e32 v15, v16, v15
	v_mul_f32_e32 v15, v17, v15
	v_cvt_pk_bf16_f32 v14, v14, v15
	v_mul_f32_e32 v15, 0xbfb8aa3b, v10
	v_exp_f32_e32 v15, v15
	s_nop 0
	v_add_f32_e32 v15, 1.0, v15
	v_rcp_f32_e32 v15, v15
	s_nop 0
	v_mul_f32_e32 v10, v10, v15
	v_mul_f32_e32 v10, v11, v10
	v_mul_f32_e32 v11, 0xbfb8aa3b, v12
	v_exp_f32_e32 v11, v11
	s_nop 0
	v_add_f32_e32 v11, 1.0, v11
	v_rcp_f32_e32 v11, v11
	s_nop 0
	v_mul_f32_e32 v11, v12, v11
	v_mul_f32_e32 v11, v13, v11
	v_cvt_pk_bf16_f32 v15, v10, v11
	v_mul_f32_e32 v10, 0xbfb8aa3b, v6
	v_exp_f32_e32 v10, v10
	global_store_dwordx2 v[18:19], v[14:15], off
	v_add_f32_e32 v10, 1.0, v10
	v_rcp_f32_e32 v10, v10
	s_nop 0
	v_mul_f32_e32 v6, v6, v10
	v_mul_f32_e32 v6, v7, v6
	v_mul_f32_e32 v7, 0xbfb8aa3b, v8
	v_exp_f32_e32 v7, v7
	s_nop 0
	v_add_f32_e32 v7, 1.0, v7
	v_rcp_f32_e32 v7, v7
	s_nop 0
	v_mul_f32_e32 v7, v8, v7
	v_mul_f32_e32 v7, v9, v7
	v_cvt_pk_bf16_f32 v6, v6, v7
	v_mul_f32_e32 v7, 0xbfb8aa3b, v2
	v_exp_f32_e32 v7, v7
	s_nop 0
	v_add_f32_e32 v7, 1.0, v7
	v_rcp_f32_e32 v7, v7
	s_nop 0
	v_mul_f32_e32 v2, v2, v7
	v_mul_f32_e32 v2, v3, v2
	v_mul_f32_e32 v3, 0xbfb8aa3b, v4
	v_exp_f32_e32 v3, v3
	s_nop 0
	v_add_f32_e32 v3, 1.0, v3
	v_rcp_f32_e32 v3, v3
	s_nop 0
	v_mul_f32_e32 v3, v4, v3
	v_mul_f32_e32 v3, v5, v3
	v_cvt_pk_bf16_f32 v7, v2, v3
	global_store_dwordx2 v[18:19], v[6:7], off offset:128
	s_cbranch_vccnz .LBB0_4832
	s_andn2_b64 vcc, exec, s[14:15]
	s_cbranch_vccnz .LBB0_4831
	s_barrier
	s_branch .LBB0_4831
